# L2 GEMM staging via LDS-DMA into double-buffered XOR-swizzled LDS (1 barrier per k-step); lora stage-2 loop prefetches next trip fragments ahead of stores; mlstm_passA and ssd_passA staging loops unro
# speedup vs baseline: 1.1121x; 1.0322x over previous
.LBB0_257:
	v_readlane_b32 s4, v250, 43
	v_readlane_b32 s5, v250, 44
	s_mov_b32 s2, s85
	v_mov_b32_e32 v0, v172
	s_and_b64 vcc, exec, s[4:5]
	s_cbranch_vccz .LBB0_262
	s_mul_hi_i32 s4, s2, 0x740000
	s_mul_i32 s5, s2, 0x740000
	v_readlane_b32 s2, v250, 32
	s_add_u32 s2, s2, s5
	v_readlane_b32 s3, v250, 33
	v_lshlrev_b32_e32 v3, 4, v0
	v_ashrrev_i32_e32 v5, 1, v0
	s_addc_u32 s3, s3, s4
	v_and_b32_e32 v4, 15, v0
	v_and_b32_e32 v2, 64, v0
	v_and_b32_e32 v148, 0x70, v3
	v_and_b32_e32 v3, 0x4f, v0
	v_and_b32_e32 v5, 0xffffffc0, v5
	v_ashrrev_i32_e32 v110, 3, v0
	v_bfe_u32 v1, v0, 4, 2
	v_lshl_add_u64 v[98:99], s[2:3], 0, v[148:149]
	v_or_b32_e32 v7, v5, v4
	v_mul_u32_u24_e32 v9, 0x90, v3
	v_lshlrev_b32_e32 v2, 2, v2
	v_mov_b32_e32 v3, v149
	v_and_b32_e32 v0, 7, v0
	s_add_u32 s2, s82, s5
	v_lshlrev_b32_e32 v6, 4, v1
	v_lshl_or_b32 v111, v1, 2, v5
	v_mul_lo_u32 v8, v110, s33
	v_mul_lo_u32 v7, v7, s33
	v_lshl_add_u64 v[2:3], s[94:95], 0, v[2:3]
	v_lshlrev_b32_e32 v4, 2, v4
	v_mov_b32_e32 v5, v149
	v_lshlrev_b32_e32 v0, 4, v0
	v_mov_b32_e32 v1, v149
	s_addc_u32 s3, s83, s4
	v_lshl_add_u64 v[96:97], s[90:91], 0, v[148:149]
	v_lshl_add_u64 v[100:101], v[2:3], 0, v[4:5]
	v_lshl_add_u64 v[102:103], s[82:83], 0, v[0:1]
	v_lshl_add_u64 v[104:105], s[2:3], 0, v[0:1]
	v_add_u32_e32 v112, v148, v8
	v_add_u32_e32 v113, v6, v9
	v_add_u32_e32 v114, v6, v7
	v_readlane_b32 s6, v247, 34
	v_lshrrev_b32_e32 v160, 6, v172
	s_nop 0
	v_readfirstlane_b32 s58, v160
	s_nop 3
	s_lshl_b32 s58, s58, 12
	s_mul_i32 s62, s85, 0x740000
	s_add_u32 s60, s82, s62
	s_addc_u32 s61, s83, 0
	s_add_u32 s60, s60, 0x10e00000
	s_addc_u32 s61, s61, 0
	v_and_b32_e32 v160, 63, v172
	v_lshrrev_b32_e32 v161, 3, v160
	v_lshrrev_b32_e32 v162, 6, v172
	v_lshl_add_u32 v161, v162, 5, v161
	v_lshlrev_b32_e32 v161, 11, v161
	v_and_b32_e32 v162, 7, v160
	v_lshrrev_b32_e32 v163, 4, v160
	v_xor_b32_e32 v162, v162, v163
	v_lshl_add_u32 v152, v162, 4, v161
	v_xor_b32_e32 v163, 4, v162
	v_lshl_add_u32 v153, v163, 4, v161
	v_add_u32_e32 v153, 0x4000, v153
	v_add_u32_e32 v154, 0x8000, v152
	v_add_u32_e32 v155, 0x8000, v153
	v_and_b32_e32 v160, 15, v172
	v_lshrrev_b32_e32 v161, 1, v160
	v_and_b32_e32 v161, 7, v161
	v_bfe_u32 v162, v172, 4, 2
	v_xor_b32_e32 v161, v161, v162
	v_lshlrev_b32_e32 v161, 4, v161
	v_lshl_add_u32 v161, v160, 7, v161
	v_lshrrev_b32_e32 v162, 7, v172
	v_lshl_add_u32 v156, v162, 13, v161
	v_xor_b32_e32 v157, 64, v156
	v_bfe_u32 v162, v172, 6, 1
	v_lshl_add_u32 v158, v162, 13, v161
	v_xor_b32_e32 v159, 64, v158
.LBB0_259:
	s_add_i32 s2, s6, s22
	s_mul_hi_i32 s3, s2, 0x8d3dcb09
	s_add_i32 s3, s3, s2
	s_lshr_b32 s4, s3, 31
	s_ashr_i32 s3, s3, 4
	s_add_i32 s3, s3, s4
	s_mul_i32 s4, s3, 29
	s_lshl_b32 s3, s3, 7
	s_sub_i32 s2, s2, s4
	s_lshl_b32 s2, s2, 7
	s_lshl_b32 s62, s3, 11
	s_add_u32 s54, s82, s62
	s_addc_u32 s55, s83, 0
	s_add_u32 s54, s54, 0x3000000
	s_addc_u32 s55, s55, 0
	s_lshl_b32 s62, s2, 11
	s_add_u32 s56, s60, s62
	s_addc_u32 s57, s61, 0
	s_add_u32 m0, s58, 0x0
	s_nop 0
	global_load_lds_dwordx4 v152, s[54:55]
	s_add_u32 m0, m0, 0x400
	s_nop 0
	global_load_lds_dwordx4 v153, s[54:55]
	s_add_u32 m0, m0, 0x400
	s_nop 0
	global_load_lds_dwordx4 v154, s[54:55]
	s_add_u32 m0, m0, 0x400
	s_nop 0
	global_load_lds_dwordx4 v155, s[54:55]
	s_add_u32 m0, m0, 0x3400
	s_nop 0
	global_load_lds_dwordx4 v152, s[56:57]
	s_add_u32 m0, m0, 0x400
	s_nop 0
	global_load_lds_dwordx4 v153, s[56:57]
	s_add_u32 m0, m0, 0x400
	s_nop 0
	global_load_lds_dwordx4 v154, s[56:57]
	s_add_u32 m0, m0, 0x400
	s_nop 0
	global_load_lds_dwordx4 v155, s[56:57]
	v_mov_b32_e32 v60, 0
	v_mov_b32_e32 v61, v60
	v_mov_b32_e32 v62, v60
	v_mov_b32_e32 v63, v60
	v_mov_b32_e32 v40, v60
	v_mov_b32_e32 v41, v60
	v_mov_b32_e32 v42, v60
	v_mov_b32_e32 v43, v60
	v_mov_b32_e32 v44, v60
	v_mov_b32_e32 v45, v60
	v_mov_b32_e32 v46, v60
	v_mov_b32_e32 v47, v60
	v_mov_b32_e32 v48, v60
	v_mov_b32_e32 v49, v60
	v_mov_b32_e32 v50, v60
	v_mov_b32_e32 v51, v60
	v_mov_b32_e32 v52, v60
	v_mov_b32_e32 v53, v60
	v_mov_b32_e32 v54, v60
	v_mov_b32_e32 v55, v60
	v_mov_b32_e32 v56, v60
	v_mov_b32_e32 v57, v60
	v_mov_b32_e32 v58, v60
	v_mov_b32_e32 v59, v60
	v_mov_b32_e32 v16, v60
	v_mov_b32_e32 v17, v60
	v_mov_b32_e32 v18, v60
	v_mov_b32_e32 v19, v60
	v_mov_b32_e32 v12, v60
	v_mov_b32_e32 v13, v60
	v_mov_b32_e32 v14, v60
	v_mov_b32_e32 v15, v60
	v_mov_b32_e32 v20, v60
	v_mov_b32_e32 v21, v60
	v_mov_b32_e32 v22, v60
	v_mov_b32_e32 v23, v60
	v_mov_b32_e32 v0, v60
	v_mov_b32_e32 v1, v60
	v_mov_b32_e32 v2, v60
	v_mov_b32_e32 v3, v60
	v_mov_b32_e32 v4, v60
	v_mov_b32_e32 v5, v60
	v_mov_b32_e32 v6, v60
	v_mov_b32_e32 v7, v60
	v_mov_b32_e32 v8, v60
	v_mov_b32_e32 v9, v60
	v_mov_b32_e32 v10, v60
	v_mov_b32_e32 v11, v60
	v_mov_b32_e32 v24, v60
	v_mov_b32_e32 v25, v60
	v_mov_b32_e32 v26, v60
	v_mov_b32_e32 v27, v60
	v_mov_b32_e32 v28, v60
	v_mov_b32_e32 v29, v60
	v_mov_b32_e32 v30, v60
	v_mov_b32_e32 v31, v60
	v_mov_b32_e32 v32, v60
	v_mov_b32_e32 v33, v60
	v_mov_b32_e32 v34, v60
	v_mov_b32_e32 v35, v60
	v_mov_b32_e32 v36, v60
	v_mov_b32_e32 v37, v60
	v_mov_b32_e32 v38, v60
	v_mov_b32_e32 v39, v60
	s_mov_b32 s59, 8
	s_waitcnt vmcnt(0)
	s_barrier
.Lg2_loop:
	s_add_u32 s54, s54, 0x80
	s_addc_u32 s55, s55, 0
	s_add_u32 s56, s56, 0x80
	s_addc_u32 s57, s57, 0
	ds_read_b128 v[64:67], v156
	ds_read_b128 v[68:71], v158 offset:16384
	ds_read_b128 v[80:83], v159 offset:16384
	ds_read_b128 v[72:75], v157
	ds_read_b128 v[76:79], v158 offset:18432
	ds_read_b128 v[92:95], v159 offset:18432
	ds_read_b128 v[84:87], v158 offset:20480
	ds_read_b128 v[116:119], v159 offset:20480
	ds_read_b128 v[88:91], v158 offset:22528
	ds_read_b128 v[120:123], v159 offset:22528
	s_waitcnt lgkmcnt(8)
	v_mfma_f32_16x16x32_bf16 v[36:39], v[64:67], v[68:71], v[36:39]
	s_waitcnt lgkmcnt(5)
	v_mfma_f32_16x16x32_bf16 v[32:35], v[64:67], v[76:79], v[32:35]
	s_waitcnt lgkmcnt(3)
	s_add_u32 m0, s58, 0x8000
	v_mfma_f32_16x16x32_bf16 v[28:31], v[64:67], v[84:87], v[28:31]
	global_load_lds_dwordx4 v152, s[54:55]
	s_waitcnt lgkmcnt(1)
	v_mfma_f32_16x16x32_bf16 v[24:27], v[64:67], v[88:91], v[24:27]
	ds_read_b128 v[64:67], v156 offset:2048
	ds_read_b128 v[124:127], v157 offset:2048
	s_waitcnt lgkmcnt(1)
	v_mfma_f32_16x16x32_bf16 v[8:11], v[64:67], v[68:71], v[8:11]
	s_add_u32 m0, m0, 0x400
	v_mfma_f32_16x16x32_bf16 v[4:7], v[64:67], v[76:79], v[4:7]
	global_load_lds_dwordx4 v153, s[54:55]
	v_mfma_f32_16x16x32_bf16 v[0:3], v[64:67], v[84:87], v[0:3]
	v_mfma_f32_16x16x32_bf16 v[20:23], v[64:67], v[88:91], v[20:23]
	ds_read_b128 v[64:67], v156 offset:4096
	ds_read_b128 v[128:131], v157 offset:4096
	s_waitcnt lgkmcnt(1)
	s_add_u32 m0, m0, 0x400
	v_mfma_f32_16x16x32_bf16 v[12:15], v[64:67], v[68:71], v[12:15]
	global_load_lds_dwordx4 v154, s[54:55]
	v_mfma_f32_16x16x32_bf16 v[16:19], v[64:67], v[76:79], v[16:19]
	v_mfma_f32_16x16x32_bf16 v[56:59], v[64:67], v[84:87], v[56:59]
	s_add_u32 m0, m0, 0x400
	v_mfma_f32_16x16x32_bf16 v[52:55], v[64:67], v[88:91], v[52:55]
	global_load_lds_dwordx4 v155, s[54:55]
	ds_read_b128 v[64:67], v156 offset:6144
	ds_read_b128 v[132:135], v157 offset:6144
	s_waitcnt lgkmcnt(1)
	v_mfma_f32_16x16x32_bf16 v[48:51], v[64:67], v[68:71], v[48:51]
	v_mfma_f32_16x16x32_bf16 v[44:47], v[64:67], v[76:79], v[44:47]
	s_add_u32 m0, m0, 0x3400
	v_mfma_f32_16x16x32_bf16 v[40:43], v[64:67], v[84:87], v[40:43]
	global_load_lds_dwordx4 v152, s[56:57]
	v_mfma_f32_16x16x32_bf16 v[60:63], v[64:67], v[88:91], v[60:63]
	v_mfma_f32_16x16x32_bf16 v[36:39], v[72:75], v[80:83], v[36:39]
	s_add_u32 m0, m0, 0x400
	v_mfma_f32_16x16x32_bf16 v[32:35], v[72:75], v[92:95], v[32:35]
	global_load_lds_dwordx4 v153, s[56:57]
	v_mfma_f32_16x16x32_bf16 v[28:31], v[72:75], v[116:119], v[28:31]
	v_mfma_f32_16x16x32_bf16 v[24:27], v[72:75], v[120:123], v[24:27]
	s_add_u32 m0, m0, 0x400
	v_mfma_f32_16x16x32_bf16 v[8:11], v[124:127], v[80:83], v[8:11]
	global_load_lds_dwordx4 v154, s[56:57]
	v_mfma_f32_16x16x32_bf16 v[4:7], v[124:127], v[92:95], v[4:7]
	v_mfma_f32_16x16x32_bf16 v[0:3], v[124:127], v[116:119], v[0:3]
	s_add_u32 m0, m0, 0x400
	v_mfma_f32_16x16x32_bf16 v[20:23], v[124:127], v[120:123], v[20:23]
	global_load_lds_dwordx4 v155, s[56:57]
	v_mfma_f32_16x16x32_bf16 v[12:15], v[128:131], v[80:83], v[12:15]
	s_waitcnt lgkmcnt(0)
	v_mfma_f32_16x16x32_bf16 v[48:51], v[132:135], v[80:83], v[48:51]
	v_mfma_f32_16x16x32_bf16 v[16:19], v[128:131], v[92:95], v[16:19]
	v_mfma_f32_16x16x32_bf16 v[44:47], v[132:135], v[92:95], v[44:47]
	v_mfma_f32_16x16x32_bf16 v[56:59], v[128:131], v[116:119], v[56:59]
	v_mfma_f32_16x16x32_bf16 v[52:55], v[128:131], v[120:123], v[52:55]
	v_mfma_f32_16x16x32_bf16 v[40:43], v[132:135], v[116:119], v[40:43]
	v_mfma_f32_16x16x32_bf16 v[60:63], v[132:135], v[120:123], v[60:63]
	s_waitcnt vmcnt(0)
	s_barrier
	s_add_u32 s54, s54, 0x80
	s_addc_u32 s55, s55, 0
	s_add_u32 s56, s56, 0x80
	s_addc_u32 s57, s57, 0
	ds_read_b128 v[64:67], v156 offset:32768
	ds_read_b128 v[68:71], v158 offset:49152
	ds_read_b128 v[80:83], v159 offset:49152
	ds_read_b128 v[72:75], v157 offset:32768
	ds_read_b128 v[76:79], v158 offset:51200
	ds_read_b128 v[92:95], v159 offset:51200
	ds_read_b128 v[84:87], v158 offset:53248
	ds_read_b128 v[116:119], v159 offset:53248
	ds_read_b128 v[88:91], v158 offset:55296
	ds_read_b128 v[120:123], v159 offset:55296
	s_waitcnt lgkmcnt(8)
	v_mfma_f32_16x16x32_bf16 v[36:39], v[64:67], v[68:71], v[36:39]
	s_waitcnt lgkmcnt(5)
	v_mfma_f32_16x16x32_bf16 v[32:35], v[64:67], v[76:79], v[32:35]
	s_waitcnt lgkmcnt(3)
	s_add_u32 m0, s58, 0x0
	v_mfma_f32_16x16x32_bf16 v[28:31], v[64:67], v[84:87], v[28:31]
	global_load_lds_dwordx4 v152, s[54:55]
	s_waitcnt lgkmcnt(1)
	v_mfma_f32_16x16x32_bf16 v[24:27], v[64:67], v[88:91], v[24:27]
	ds_read_b128 v[64:67], v156 offset:34816
	ds_read_b128 v[124:127], v157 offset:34816
	s_waitcnt lgkmcnt(1)
	v_mfma_f32_16x16x32_bf16 v[8:11], v[64:67], v[68:71], v[8:11]
	s_add_u32 m0, m0, 0x400
	v_mfma_f32_16x16x32_bf16 v[4:7], v[64:67], v[76:79], v[4:7]
	global_load_lds_dwordx4 v153, s[54:55]
	v_mfma_f32_16x16x32_bf16 v[0:3], v[64:67], v[84:87], v[0:3]
	v_mfma_f32_16x16x32_bf16 v[20:23], v[64:67], v[88:91], v[20:23]
	ds_read_b128 v[64:67], v156 offset:36864
	ds_read_b128 v[128:131], v157 offset:36864
	s_waitcnt lgkmcnt(1)
	s_add_u32 m0, m0, 0x400
	v_mfma_f32_16x16x32_bf16 v[12:15], v[64:67], v[68:71], v[12:15]
	global_load_lds_dwordx4 v154, s[54:55]
	v_mfma_f32_16x16x32_bf16 v[16:19], v[64:67], v[76:79], v[16:19]
	v_mfma_f32_16x16x32_bf16 v[56:59], v[64:67], v[84:87], v[56:59]
	s_add_u32 m0, m0, 0x400
	v_mfma_f32_16x16x32_bf16 v[52:55], v[64:67], v[88:91], v[52:55]
	global_load_lds_dwordx4 v155, s[54:55]
	ds_read_b128 v[64:67], v156 offset:38912
	ds_read_b128 v[132:135], v157 offset:38912
	s_waitcnt lgkmcnt(1)
	v_mfma_f32_16x16x32_bf16 v[48:51], v[64:67], v[68:71], v[48:51]
	v_mfma_f32_16x16x32_bf16 v[44:47], v[64:67], v[76:79], v[44:47]
	s_add_u32 m0, m0, 0x3400
	v_mfma_f32_16x16x32_bf16 v[40:43], v[64:67], v[84:87], v[40:43]
	global_load_lds_dwordx4 v152, s[56:57]
	v_mfma_f32_16x16x32_bf16 v[60:63], v[64:67], v[88:91], v[60:63]
	v_mfma_f32_16x16x32_bf16 v[36:39], v[72:75], v[80:83], v[36:39]
	s_add_u32 m0, m0, 0x400
	v_mfma_f32_16x16x32_bf16 v[32:35], v[72:75], v[92:95], v[32:35]
	global_load_lds_dwordx4 v153, s[56:57]
	v_mfma_f32_16x16x32_bf16 v[28:31], v[72:75], v[116:119], v[28:31]
	v_mfma_f32_16x16x32_bf16 v[24:27], v[72:75], v[120:123], v[24:27]
	s_add_u32 m0, m0, 0x400
	v_mfma_f32_16x16x32_bf16 v[8:11], v[124:127], v[80:83], v[8:11]
	global_load_lds_dwordx4 v154, s[56:57]
	v_mfma_f32_16x16x32_bf16 v[4:7], v[124:127], v[92:95], v[4:7]
	v_mfma_f32_16x16x32_bf16 v[0:3], v[124:127], v[116:119], v[0:3]
	s_add_u32 m0, m0, 0x400
	v_mfma_f32_16x16x32_bf16 v[20:23], v[124:127], v[120:123], v[20:23]
	global_load_lds_dwordx4 v155, s[56:57]
	v_mfma_f32_16x16x32_bf16 v[12:15], v[128:131], v[80:83], v[12:15]
	s_waitcnt lgkmcnt(0)
	v_mfma_f32_16x16x32_bf16 v[48:51], v[132:135], v[80:83], v[48:51]
	v_mfma_f32_16x16x32_bf16 v[16:19], v[128:131], v[92:95], v[16:19]
	v_mfma_f32_16x16x32_bf16 v[44:47], v[132:135], v[92:95], v[44:47]
	v_mfma_f32_16x16x32_bf16 v[56:59], v[128:131], v[116:119], v[56:59]
	v_mfma_f32_16x16x32_bf16 v[52:55], v[128:131], v[120:123], v[52:55]
	v_mfma_f32_16x16x32_bf16 v[40:43], v[132:135], v[116:119], v[40:43]
	v_mfma_f32_16x16x32_bf16 v[60:63], v[132:135], v[120:123], v[60:63]
	s_waitcnt vmcnt(0)
	s_barrier
	s_add_i32 s59, s59, -1
	s_cmp_lg_u32 s59, 0
	s_cbranch_scc1 .Lg2_loop
	s_nop 7
	s_nop 7
	s_movk_i32 s4, 0x3a00
	s_add_i32 s6, s6, s92
	v_add_u32_e32 v68, s3, v111
	s_ashr_i32 s3, s2, 31
	v_lshl_add_u64 v[64:65], s[2:3], 2, v[100:101]
	v_mad_i64_i32 v[66:67], s[2:3], v68, s4, v[64:65]
	global_store_dword v[66:67], v36, off
	global_store_dword v[66:67], v32, off offset:64
	global_store_dword v[66:67], v28, off offset:128
	global_store_dword v[66:67], v24, off offset:192
	v_or_b32_e32 v24, 1, v68
	v_mad_i64_i32 v[66:67], s[2:3], v24, s4, v[64:65]
	v_or_b32_e32 v24, 2, v68
	global_store_dword v[66:67], v37, off
	global_store_dword v[66:67], v33, off offset:64
	global_store_dword v[66:67], v29, off offset:128
	global_store_dword v[66:67], v25, off offset:192
	v_mad_i64_i32 v[24:25], s[2:3], v24, s4, v[64:65]
	global_store_dword v[24:25], v38, off
	global_store_dword v[24:25], v34, off offset:64
	global_store_dword v[24:25], v30, off offset:128
	global_store_dword v[24:25], v26, off offset:192
	v_or_b32_e32 v24, 3, v68
	v_mad_i64_i32 v[24:25], s[2:3], v24, s4, v[64:65]
	global_store_dword v[24:25], v39, off
	global_store_dword v[24:25], v35, off offset:64
	global_store_dword v[24:25], v31, off offset:128
	global_store_dword v[24:25], v27, off offset:192
	v_or_b32_e32 v24, 16, v68
	v_mad_i64_i32 v[24:25], s[2:3], v24, s4, v[64:65]
	global_store_dword v[24:25], v8, off
	global_store_dword v[24:25], v4, off offset:64
	global_store_dword v[24:25], v0, off offset:128
	global_store_dword v[24:25], v20, off offset:192
	v_or_b32_e32 v0, 17, v68
	v_mad_i64_i32 v[24:25], s[2:3], v0, s4, v[64:65]
	v_or_b32_e32 v0, 18, v68
	global_store_dword v[24:25], v9, off
	global_store_dword v[24:25], v5, off offset:64
	global_store_dword v[24:25], v1, off offset:128
	global_store_dword v[24:25], v21, off offset:192
	v_mad_i64_i32 v[0:1], s[2:3], v0, s4, v[64:65]
	global_store_dword v[0:1], v10, off
	global_store_dword v[0:1], v6, off offset:64
	global_store_dword v[0:1], v2, off offset:128
	global_store_dword v[0:1], v22, off offset:192
	v_or_b32_e32 v0, 19, v68
	v_mad_i64_i32 v[0:1], s[2:3], v0, s4, v[64:65]
	global_store_dword v[0:1], v11, off
	global_store_dword v[0:1], v7, off offset:64
	global_store_dword v[0:1], v3, off offset:128
	global_store_dword v[0:1], v23, off offset:192
	v_or_b32_e32 v0, 32, v68
	v_mad_i64_i32 v[0:1], s[2:3], v0, s4, v[64:65]
	global_store_dword v[0:1], v12, off
	global_store_dword v[0:1], v16, off offset:64
	global_store_dword v[0:1], v56, off offset:128
	global_store_dword v[0:1], v52, off offset:192
	v_or_b32_e32 v0, 33, v68
	v_mad_i64_i32 v[0:1], s[2:3], v0, s4, v[64:65]
	global_store_dword v[0:1], v13, off
	global_store_dword v[0:1], v17, off offset:64
	global_store_dword v[0:1], v57, off offset:128
	global_store_dword v[0:1], v53, off offset:192
	v_or_b32_e32 v0, 34, v68
	v_mad_i64_i32 v[0:1], s[2:3], v0, s4, v[64:65]
	global_store_dword v[0:1], v14, off
	global_store_dword v[0:1], v18, off offset:64
	global_store_dword v[0:1], v58, off offset:128
	global_store_dword v[0:1], v54, off offset:192
	v_or_b32_e32 v0, 35, v68
	v_mad_i64_i32 v[0:1], s[2:3], v0, s4, v[64:65]
	global_store_dword v[0:1], v15, off
	global_store_dword v[0:1], v19, off offset:64
	global_store_dword v[0:1], v59, off offset:128
	global_store_dword v[0:1], v55, off offset:192
	v_or_b32_e32 v0, 48, v68
	v_mad_i64_i32 v[0:1], s[2:3], v0, s4, v[64:65]
	global_store_dword v[0:1], v48, off
	global_store_dword v[0:1], v44, off offset:64
	global_store_dword v[0:1], v40, off offset:128
	s_nop 4
	global_store_dword v[0:1], v60, off offset:192
	v_or_b32_e32 v0, 49, v68
	v_mad_i64_i32 v[0:1], s[2:3], v0, s4, v[64:65]
	global_store_dword v[0:1], v49, off
	global_store_dword v[0:1], v45, off offset:64
	global_store_dword v[0:1], v41, off offset:128
	global_store_dword v[0:1], v61, off offset:192
	v_or_b32_e32 v0, 50, v68
	v_mad_i64_i32 v[0:1], s[2:3], v0, s4, v[64:65]
	global_store_dword v[0:1], v50, off
	global_store_dword v[0:1], v46, off offset:64
	global_store_dword v[0:1], v42, off offset:128
	global_store_dword v[0:1], v62, off offset:192
	v_or_b32_e32 v0, 51, v68
	v_mad_i64_i32 v[0:1], s[2:3], v0, s4, v[64:65]
	s_cmp_ge_i32 s6, s21
	global_store_dword v[0:1], v51, off
	global_store_dword v[0:1], v47, off offset:64
	global_store_dword v[0:1], v43, off offset:128
	global_store_dword v[0:1], v63, off offset:192
	s_cbranch_scc0 .LBB0_259

.LBB0_359:
	v_mov_b32_e32 v88, v3
	v_ashrrev_i32_e32 v89, 6, v88
	v_lshlrev_b32_e32 v90, 2, v89
	ds_read_b32 v91, v90 offset:28160
	ds_read2st64_b32 v[92:93], v90 offset0:108 offset1:109
	v_add_lshl_u32 v89, v89, v2, 1
	v_mov_b64_e32 v[94:95], s[94:95]
	v_add_u32_e32 v98, 0x100, v3
	v_ashrrev_i32_e32 v99, 6, v98
	v_lshlrev_b32_e32 v100, 2, v99
	ds_read_b32 v101, v100 offset:28160
	ds_read2st64_b32 v[102:103], v100 offset0:108 offset1:109
	v_add_lshl_u32 v99, v99, v2, 1
	v_mov_b64_e32 v[104:105], s[94:95]
	v_add_u32_e32 v108, 0x200, v3
	v_ashrrev_i32_e32 v109, 6, v108
	v_lshlrev_b32_e32 v110, 2, v109
	ds_read_b32 v111, v110 offset:28160
	ds_read2st64_b32 v[112:113], v110 offset0:108 offset1:109
	v_add_lshl_u32 v109, v109, v2, 1
	v_mov_b64_e32 v[114:115], s[94:95]
	v_add_u32_e32 v118, 0x300, v3
	v_ashrrev_i32_e32 v119, 6, v118
	v_lshlrev_b32_e32 v120, 2, v119
	ds_read_b32 v121, v120 offset:28160
	ds_read2st64_b32 v[122:123], v120 offset0:108 offset1:109
	v_add_lshl_u32 v119, v119, v2, 1
	v_mov_b64_e32 v[124:125], s[94:95]
	v_add_u32_e32 v128, 0x400, v3
	v_ashrrev_i32_e32 v129, 6, v128
	v_lshlrev_b32_e32 v130, 2, v129
	ds_read_b32 v131, v130 offset:28160
	ds_read2st64_b32 v[132:133], v130 offset0:108 offset1:109
	v_add_lshl_u32 v129, v129, v2, 1
	v_mov_b64_e32 v[134:135], s[94:95]
	v_add_u32_e32 v152, 0x500, v3
	v_ashrrev_i32_e32 v153, 6, v152
	v_lshlrev_b32_e32 v154, 2, v153
	ds_read_b32 v155, v154 offset:28160
	ds_read2st64_b32 v[156:157], v154 offset0:108 offset1:109
	v_add_lshl_u32 v153, v153, v2, 1
	v_mov_b64_e32 v[158:159], s[94:95]
	v_add_u32_e32 v162, 0x600, v3
	v_ashrrev_i32_e32 v163, 6, v162
	v_lshlrev_b32_e32 v164, 2, v163
	ds_read_b32 v165, v164 offset:28160
	ds_read2st64_b32 v[166:167], v164 offset0:108 offset1:109
	v_add_lshl_u32 v163, v163, v2, 1
	v_mov_b64_e32 v[168:169], s[94:95]
	v_add_u32_e32 v204, 0x700, v3
	v_ashrrev_i32_e32 v205, 6, v204
	v_lshlrev_b32_e32 v206, 2, v205
	ds_read_b32 v207, v206 offset:28160
	ds_read2st64_b32 v[208:209], v206 offset0:108 offset1:109
	v_add_lshl_u32 v205, v205, v2, 1
	v_mov_b64_e32 v[210:211], s[94:95]
	s_waitcnt lgkmcnt(15)
	v_mad_i64_i32 v[94:95], s[12:13], v91, s14, v[94:95]
	v_lshl_add_u64 v[94:95], v[94:95], 0, s[20:21]
	v_lshl_add_u64 v[94:95], v[94:95], 0, v[148:149]
	v_add_co_u32_e32 v94, vcc, 0x2000, v94
	s_nop 1
	v_addc_co_u32_e32 v95, vcc, 0, v95, vcc
	global_load_dword v96, v[94:95], off offset:1056
	global_load_dword v97, v[94:95], off offset:32
	s_waitcnt lgkmcnt(13)
	v_mad_i64_i32 v[104:105], s[12:13], v101, s14, v[104:105]
	v_lshl_add_u64 v[104:105], v[104:105], 0, s[20:21]
	v_lshl_add_u64 v[104:105], v[104:105], 0, v[148:149]
	v_add_co_u32_e32 v104, vcc, 0x2000, v104
	s_nop 1
	v_addc_co_u32_e32 v105, vcc, 0, v105, vcc
	global_load_dword v106, v[104:105], off offset:1056
	global_load_dword v107, v[104:105], off offset:32
	s_waitcnt lgkmcnt(11)
	v_mad_i64_i32 v[114:115], s[12:13], v111, s14, v[114:115]
	v_lshl_add_u64 v[114:115], v[114:115], 0, s[20:21]
	v_lshl_add_u64 v[114:115], v[114:115], 0, v[148:149]
	v_add_co_u32_e32 v114, vcc, 0x2000, v114
	s_nop 1
	v_addc_co_u32_e32 v115, vcc, 0, v115, vcc
	global_load_dword v116, v[114:115], off offset:1056
	global_load_dword v117, v[114:115], off offset:32
	s_waitcnt lgkmcnt(9)
	v_mad_i64_i32 v[124:125], s[12:13], v121, s14, v[124:125]
	v_lshl_add_u64 v[124:125], v[124:125], 0, s[20:21]
	v_lshl_add_u64 v[124:125], v[124:125], 0, v[148:149]
	v_add_co_u32_e32 v124, vcc, 0x2000, v124
	s_nop 1
	v_addc_co_u32_e32 v125, vcc, 0, v125, vcc
	global_load_dword v126, v[124:125], off offset:1056
	global_load_dword v127, v[124:125], off offset:32
	s_waitcnt lgkmcnt(7)
	v_mad_i64_i32 v[134:135], s[12:13], v131, s14, v[134:135]
	v_lshl_add_u64 v[134:135], v[134:135], 0, s[20:21]
	v_lshl_add_u64 v[134:135], v[134:135], 0, v[148:149]
	v_add_co_u32_e32 v134, vcc, 0x2000, v134
	s_nop 1
	v_addc_co_u32_e32 v135, vcc, 0, v135, vcc
	global_load_dword v136, v[134:135], off offset:1056
	global_load_dword v137, v[134:135], off offset:32
	s_waitcnt lgkmcnt(5)
	v_mad_i64_i32 v[158:159], s[12:13], v155, s14, v[158:159]
	v_lshl_add_u64 v[158:159], v[158:159], 0, s[20:21]
	v_lshl_add_u64 v[158:159], v[158:159], 0, v[148:149]
	v_add_co_u32_e32 v158, vcc, 0x2000, v158
	s_nop 1
	v_addc_co_u32_e32 v159, vcc, 0, v159, vcc
	global_load_dword v160, v[158:159], off offset:1056
	global_load_dword v161, v[158:159], off offset:32
	s_waitcnt lgkmcnt(3)
	v_mad_i64_i32 v[168:169], s[12:13], v165, s14, v[168:169]
	v_lshl_add_u64 v[168:169], v[168:169], 0, s[20:21]
	v_lshl_add_u64 v[168:169], v[168:169], 0, v[148:149]
	v_add_co_u32_e32 v168, vcc, 0x2000, v168
	s_nop 1
	v_addc_co_u32_e32 v169, vcc, 0, v169, vcc
	global_load_dword v170, v[168:169], off offset:1056
	global_load_dword v171, v[168:169], off offset:32
	s_waitcnt lgkmcnt(1)
	v_mad_i64_i32 v[210:211], s[12:13], v207, s14, v[210:211]
	v_lshl_add_u64 v[210:211], v[210:211], 0, s[20:21]
	v_lshl_add_u64 v[210:211], v[210:211], 0, v[148:149]
	v_add_co_u32_e32 v210, vcc, 0x2000, v210
	s_nop 1
	v_addc_co_u32_e32 v211, vcc, 0, v211, vcc
	global_load_dword v212, v[210:211], off offset:1056
	global_load_dword v213, v[210:211], off offset:32
	s_waitcnt vmcnt(15)
	v_mul_f32_e32 v92, v96, v92
	v_bfe_u32 v90, v92, 16, 1
	v_add3_u32 v92, v92, v90, s52
	ds_write_b16_d16_hi v89, v92
	s_waitcnt vmcnt(14)
	v_mul_f32_e32 v97, 0x3e000000, v97
	v_bfe_u32 v90, v97, 16, 1
	v_add3_u32 v97, v97, v90, s52
	ds_write_b16_d16_hi v89, v97 offset:18432
	v_mul_f32_e32 v93, v96, v93
	v_bfe_u32 v90, v93, 16, 1
	v_add3_u32 v93, v93, v90, s52
	ds_write_b16_d16_hi v89, v93 offset:9216
	s_waitcnt vmcnt(13)
	v_mul_f32_e32 v102, v106, v102
	v_bfe_u32 v100, v102, 16, 1
	v_add3_u32 v102, v102, v100, s52
	ds_write_b16_d16_hi v99, v102
	s_waitcnt vmcnt(12)
	v_mul_f32_e32 v107, 0x3e000000, v107
	v_bfe_u32 v100, v107, 16, 1
	v_add3_u32 v107, v107, v100, s52
	ds_write_b16_d16_hi v99, v107 offset:18432
	v_mul_f32_e32 v103, v106, v103
	v_bfe_u32 v100, v103, 16, 1
	v_add3_u32 v103, v103, v100, s52
	ds_write_b16_d16_hi v99, v103 offset:9216
	s_waitcnt vmcnt(11)
	v_mul_f32_e32 v112, v116, v112
	v_bfe_u32 v110, v112, 16, 1
	v_add3_u32 v112, v112, v110, s52
	ds_write_b16_d16_hi v109, v112
	s_waitcnt vmcnt(10)
	v_mul_f32_e32 v117, 0x3e000000, v117
	v_bfe_u32 v110, v117, 16, 1
	v_add3_u32 v117, v117, v110, s52
	ds_write_b16_d16_hi v109, v117 offset:18432
	v_mul_f32_e32 v113, v116, v113
	v_bfe_u32 v110, v113, 16, 1
	v_add3_u32 v113, v113, v110, s52
	ds_write_b16_d16_hi v109, v113 offset:9216
	s_waitcnt vmcnt(9)
	v_mul_f32_e32 v122, v126, v122
	v_bfe_u32 v120, v122, 16, 1
	v_add3_u32 v122, v122, v120, s52
	ds_write_b16_d16_hi v119, v122
	s_waitcnt vmcnt(8)
	v_mul_f32_e32 v127, 0x3e000000, v127
	v_bfe_u32 v120, v127, 16, 1
	v_add3_u32 v127, v127, v120, s52
	ds_write_b16_d16_hi v119, v127 offset:18432
	v_mul_f32_e32 v123, v126, v123
	v_bfe_u32 v120, v123, 16, 1
	v_add3_u32 v123, v123, v120, s52
	ds_write_b16_d16_hi v119, v123 offset:9216
	s_waitcnt vmcnt(7)
	v_mul_f32_e32 v132, v136, v132
	v_bfe_u32 v130, v132, 16, 1
	v_add3_u32 v132, v132, v130, s52
	ds_write_b16_d16_hi v129, v132
	s_waitcnt vmcnt(6)
	v_mul_f32_e32 v137, 0x3e000000, v137
	v_bfe_u32 v130, v137, 16, 1
	v_add3_u32 v137, v137, v130, s52
	ds_write_b16_d16_hi v129, v137 offset:18432
	v_mul_f32_e32 v133, v136, v133
	v_bfe_u32 v130, v133, 16, 1
	v_add3_u32 v133, v133, v130, s52
	ds_write_b16_d16_hi v129, v133 offset:9216
	s_waitcnt vmcnt(5)
	v_mul_f32_e32 v156, v160, v156
	v_bfe_u32 v154, v156, 16, 1
	v_add3_u32 v156, v156, v154, s52
	ds_write_b16_d16_hi v153, v156
	s_waitcnt vmcnt(4)
	v_mul_f32_e32 v161, 0x3e000000, v161
	v_bfe_u32 v154, v161, 16, 1
	v_add3_u32 v161, v161, v154, s52
	ds_write_b16_d16_hi v153, v161 offset:18432
	v_mul_f32_e32 v157, v160, v157
	v_bfe_u32 v154, v157, 16, 1
	v_add3_u32 v157, v157, v154, s52
	ds_write_b16_d16_hi v153, v157 offset:9216
	s_waitcnt vmcnt(3)
	v_mul_f32_e32 v166, v170, v166
	v_bfe_u32 v164, v166, 16, 1
	v_add3_u32 v166, v166, v164, s52
	ds_write_b16_d16_hi v163, v166
	s_waitcnt vmcnt(2)
	v_mul_f32_e32 v171, 0x3e000000, v171
	v_bfe_u32 v164, v171, 16, 1
	v_add3_u32 v171, v171, v164, s52
	ds_write_b16_d16_hi v163, v171 offset:18432
	v_mul_f32_e32 v167, v170, v167
	v_bfe_u32 v164, v167, 16, 1
	v_add3_u32 v167, v167, v164, s52
	ds_write_b16_d16_hi v163, v167 offset:9216
	s_waitcnt vmcnt(1) lgkmcnt(15)
	v_mul_f32_e32 v208, v212, v208
	v_bfe_u32 v206, v208, 16, 1
	v_add3_u32 v208, v208, v206, s52
	ds_write_b16_d16_hi v205, v208
	s_waitcnt vmcnt(0)
	v_mul_f32_e32 v213, 0x3e000000, v213
	v_bfe_u32 v206, v213, 16, 1
	v_add3_u32 v213, v213, v206, s52
	ds_write_b16_d16_hi v205, v213 offset:18432
	v_mul_f32_e32 v209, v212, v209
	v_bfe_u32 v206, v209, 16, 1
	v_add3_u32 v209, v209, v206, s52
	ds_write_b16_d16_hi v205, v209 offset:9216
	v_add_u32_e32 v88, 0x800, v3
	v_ashrrev_i32_e32 v89, 6, v88
	v_lshlrev_b32_e32 v90, 2, v89
	ds_read_b32 v91, v90 offset:28160
	ds_read2st64_b32 v[92:93], v90 offset0:108 offset1:109
	v_add_lshl_u32 v89, v89, v2, 1
	v_mov_b64_e32 v[94:95], s[94:95]
	v_add_u32_e32 v98, 0x900, v3
	v_ashrrev_i32_e32 v99, 6, v98
	v_lshlrev_b32_e32 v100, 2, v99
	ds_read_b32 v101, v100 offset:28160
	ds_read2st64_b32 v[102:103], v100 offset0:108 offset1:109
	v_add_lshl_u32 v99, v99, v2, 1
	v_mov_b64_e32 v[104:105], s[94:95]
	v_add_u32_e32 v108, 0xa00, v3
	v_ashrrev_i32_e32 v109, 6, v108
	v_lshlrev_b32_e32 v110, 2, v109
	ds_read_b32 v111, v110 offset:28160
	ds_read2st64_b32 v[112:113], v110 offset0:108 offset1:109
	v_add_lshl_u32 v109, v109, v2, 1
	v_mov_b64_e32 v[114:115], s[94:95]
	v_add_u32_e32 v118, 0xb00, v3
	v_ashrrev_i32_e32 v119, 6, v118
	v_lshlrev_b32_e32 v120, 2, v119
	ds_read_b32 v121, v120 offset:28160
	ds_read2st64_b32 v[122:123], v120 offset0:108 offset1:109
	v_add_lshl_u32 v119, v119, v2, 1
	v_mov_b64_e32 v[124:125], s[94:95]
	v_add_u32_e32 v128, 0xc00, v3
	v_ashrrev_i32_e32 v129, 6, v128
	v_lshlrev_b32_e32 v130, 2, v129
	ds_read_b32 v131, v130 offset:28160
	ds_read2st64_b32 v[132:133], v130 offset0:108 offset1:109
	v_add_lshl_u32 v129, v129, v2, 1
	v_mov_b64_e32 v[134:135], s[94:95]
	v_add_u32_e32 v152, 0xd00, v3
	v_ashrrev_i32_e32 v153, 6, v152
	v_lshlrev_b32_e32 v154, 2, v153
	ds_read_b32 v155, v154 offset:28160
	ds_read2st64_b32 v[156:157], v154 offset0:108 offset1:109
	v_add_lshl_u32 v153, v153, v2, 1
	v_mov_b64_e32 v[158:159], s[94:95]
	v_add_u32_e32 v162, 0xe00, v3
	v_ashrrev_i32_e32 v163, 6, v162
	v_lshlrev_b32_e32 v164, 2, v163
	ds_read_b32 v165, v164 offset:28160
	ds_read2st64_b32 v[166:167], v164 offset0:108 offset1:109
	v_add_lshl_u32 v163, v163, v2, 1
	v_mov_b64_e32 v[168:169], s[94:95]
	v_add_u32_e32 v204, 0xf00, v3
	v_ashrrev_i32_e32 v205, 6, v204
	v_lshlrev_b32_e32 v206, 2, v205
	ds_read_b32 v207, v206 offset:28160
	ds_read2st64_b32 v[208:209], v206 offset0:108 offset1:109
	v_add_lshl_u32 v205, v205, v2, 1
	v_mov_b64_e32 v[210:211], s[94:95]
	s_waitcnt lgkmcnt(15)
	v_mad_i64_i32 v[94:95], s[12:13], v91, s14, v[94:95]
	v_lshl_add_u64 v[94:95], v[94:95], 0, s[20:21]
	v_lshl_add_u64 v[94:95], v[94:95], 0, v[148:149]
	v_add_co_u32_e32 v94, vcc, 0x2000, v94
	s_nop 1
	v_addc_co_u32_e32 v95, vcc, 0, v95, vcc
	global_load_dword v96, v[94:95], off offset:1056
	global_load_dword v97, v[94:95], off offset:32
	s_waitcnt lgkmcnt(13)
	v_mad_i64_i32 v[104:105], s[12:13], v101, s14, v[104:105]
	v_lshl_add_u64 v[104:105], v[104:105], 0, s[20:21]
	v_lshl_add_u64 v[104:105], v[104:105], 0, v[148:149]
	v_add_co_u32_e32 v104, vcc, 0x2000, v104
	s_nop 1
	v_addc_co_u32_e32 v105, vcc, 0, v105, vcc
	global_load_dword v106, v[104:105], off offset:1056
	global_load_dword v107, v[104:105], off offset:32
	s_waitcnt lgkmcnt(11)
	v_mad_i64_i32 v[114:115], s[12:13], v111, s14, v[114:115]
	v_lshl_add_u64 v[114:115], v[114:115], 0, s[20:21]
	v_lshl_add_u64 v[114:115], v[114:115], 0, v[148:149]
	v_add_co_u32_e32 v114, vcc, 0x2000, v114
	s_nop 1
	v_addc_co_u32_e32 v115, vcc, 0, v115, vcc
	global_load_dword v116, v[114:115], off offset:1056
	global_load_dword v117, v[114:115], off offset:32
	s_waitcnt lgkmcnt(9)
	v_mad_i64_i32 v[124:125], s[12:13], v121, s14, v[124:125]
	v_lshl_add_u64 v[124:125], v[124:125], 0, s[20:21]
	v_lshl_add_u64 v[124:125], v[124:125], 0, v[148:149]
	v_add_co_u32_e32 v124, vcc, 0x2000, v124
	s_nop 1
	v_addc_co_u32_e32 v125, vcc, 0, v125, vcc
	global_load_dword v126, v[124:125], off offset:1056
	global_load_dword v127, v[124:125], off offset:32
	s_waitcnt lgkmcnt(7)
	v_mad_i64_i32 v[134:135], s[12:13], v131, s14, v[134:135]
	v_lshl_add_u64 v[134:135], v[134:135], 0, s[20:21]
	v_lshl_add_u64 v[134:135], v[134:135], 0, v[148:149]
	v_add_co_u32_e32 v134, vcc, 0x2000, v134
	s_nop 1
	v_addc_co_u32_e32 v135, vcc, 0, v135, vcc
	global_load_dword v136, v[134:135], off offset:1056
	global_load_dword v137, v[134:135], off offset:32
	s_waitcnt lgkmcnt(5)
	v_mad_i64_i32 v[158:159], s[12:13], v155, s14, v[158:159]
	v_lshl_add_u64 v[158:159], v[158:159], 0, s[20:21]
	v_lshl_add_u64 v[158:159], v[158:159], 0, v[148:149]
	v_add_co_u32_e32 v158, vcc, 0x2000, v158
	s_nop 1
	v_addc_co_u32_e32 v159, vcc, 0, v159, vcc
	global_load_dword v160, v[158:159], off offset:1056
	global_load_dword v161, v[158:159], off offset:32
	s_waitcnt lgkmcnt(3)
	v_mad_i64_i32 v[168:169], s[12:13], v165, s14, v[168:169]
	v_lshl_add_u64 v[168:169], v[168:169], 0, s[20:21]
	v_lshl_add_u64 v[168:169], v[168:169], 0, v[148:149]
	v_add_co_u32_e32 v168, vcc, 0x2000, v168
	s_nop 1
	v_addc_co_u32_e32 v169, vcc, 0, v169, vcc
	global_load_dword v170, v[168:169], off offset:1056
	global_load_dword v171, v[168:169], off offset:32
	s_waitcnt lgkmcnt(1)
	v_mad_i64_i32 v[210:211], s[12:13], v207, s14, v[210:211]
	v_lshl_add_u64 v[210:211], v[210:211], 0, s[20:21]
	v_lshl_add_u64 v[210:211], v[210:211], 0, v[148:149]
	v_add_co_u32_e32 v210, vcc, 0x2000, v210
	s_nop 1
	v_addc_co_u32_e32 v211, vcc, 0, v211, vcc
	global_load_dword v212, v[210:211], off offset:1056
	global_load_dword v213, v[210:211], off offset:32
	s_waitcnt vmcnt(15)
	v_mul_f32_e32 v92, v96, v92
	v_bfe_u32 v90, v92, 16, 1
	v_add3_u32 v92, v92, v90, s52
	ds_write_b16_d16_hi v89, v92
	s_waitcnt vmcnt(14)
	v_mul_f32_e32 v97, 0x3e000000, v97
	v_bfe_u32 v90, v97, 16, 1
	v_add3_u32 v97, v97, v90, s52
	ds_write_b16_d16_hi v89, v97 offset:18432
	v_mul_f32_e32 v93, v96, v93
	v_bfe_u32 v90, v93, 16, 1
	v_add3_u32 v93, v93, v90, s52
	ds_write_b16_d16_hi v89, v93 offset:9216
	s_waitcnt vmcnt(13)
	v_mul_f32_e32 v102, v106, v102
	v_bfe_u32 v100, v102, 16, 1
	v_add3_u32 v102, v102, v100, s52
	ds_write_b16_d16_hi v99, v102
	s_waitcnt vmcnt(12)
	v_mul_f32_e32 v107, 0x3e000000, v107
	v_bfe_u32 v100, v107, 16, 1
	v_add3_u32 v107, v107, v100, s52
	ds_write_b16_d16_hi v99, v107 offset:18432
	v_mul_f32_e32 v103, v106, v103
	v_bfe_u32 v100, v103, 16, 1
	v_add3_u32 v103, v103, v100, s52
	ds_write_b16_d16_hi v99, v103 offset:9216
	s_waitcnt vmcnt(11)
	v_mul_f32_e32 v112, v116, v112
	v_bfe_u32 v110, v112, 16, 1
	v_add3_u32 v112, v112, v110, s52
	ds_write_b16_d16_hi v109, v112
	s_waitcnt vmcnt(10)
	v_mul_f32_e32 v117, 0x3e000000, v117
	v_bfe_u32 v110, v117, 16, 1
	v_add3_u32 v117, v117, v110, s52
	ds_write_b16_d16_hi v109, v117 offset:18432
	v_mul_f32_e32 v113, v116, v113
	v_bfe_u32 v110, v113, 16, 1
	v_add3_u32 v113, v113, v110, s52
	ds_write_b16_d16_hi v109, v113 offset:9216
	s_waitcnt vmcnt(9)
	v_mul_f32_e32 v122, v126, v122
	v_bfe_u32 v120, v122, 16, 1
	v_add3_u32 v122, v122, v120, s52
	ds_write_b16_d16_hi v119, v122
	s_waitcnt vmcnt(8)
	v_mul_f32_e32 v127, 0x3e000000, v127
	v_bfe_u32 v120, v127, 16, 1
	v_add3_u32 v127, v127, v120, s52
	ds_write_b16_d16_hi v119, v127 offset:18432
	v_mul_f32_e32 v123, v126, v123
	v_bfe_u32 v120, v123, 16, 1
	v_add3_u32 v123, v123, v120, s52
	ds_write_b16_d16_hi v119, v123 offset:9216
	s_waitcnt vmcnt(7)
	v_mul_f32_e32 v132, v136, v132
	v_bfe_u32 v130, v132, 16, 1
	v_add3_u32 v132, v132, v130, s52
	ds_write_b16_d16_hi v129, v132
	s_waitcnt vmcnt(6)
	v_mul_f32_e32 v137, 0x3e000000, v137
	v_bfe_u32 v130, v137, 16, 1
	v_add3_u32 v137, v137, v130, s52
	ds_write_b16_d16_hi v129, v137 offset:18432
	v_mul_f32_e32 v133, v136, v133
	v_bfe_u32 v130, v133, 16, 1
	v_add3_u32 v133, v133, v130, s52
	ds_write_b16_d16_hi v129, v133 offset:9216
	s_waitcnt vmcnt(5)
	v_mul_f32_e32 v156, v160, v156
	v_bfe_u32 v154, v156, 16, 1
	v_add3_u32 v156, v156, v154, s52
	ds_write_b16_d16_hi v153, v156
	s_waitcnt vmcnt(4)
	v_mul_f32_e32 v161, 0x3e000000, v161
	v_bfe_u32 v154, v161, 16, 1
	v_add3_u32 v161, v161, v154, s52
	ds_write_b16_d16_hi v153, v161 offset:18432
	v_mul_f32_e32 v157, v160, v157
	v_bfe_u32 v154, v157, 16, 1
	v_add3_u32 v157, v157, v154, s52
	ds_write_b16_d16_hi v153, v157 offset:9216
	s_waitcnt vmcnt(3)
	v_mul_f32_e32 v166, v170, v166
	v_bfe_u32 v164, v166, 16, 1
	v_add3_u32 v166, v166, v164, s52
	ds_write_b16_d16_hi v163, v166
	s_waitcnt vmcnt(2)
	v_mul_f32_e32 v171, 0x3e000000, v171
	v_bfe_u32 v164, v171, 16, 1
	v_add3_u32 v171, v171, v164, s52
	ds_write_b16_d16_hi v163, v171 offset:18432
	v_mul_f32_e32 v167, v170, v167
	v_bfe_u32 v164, v167, 16, 1
	v_add3_u32 v167, v167, v164, s52
	ds_write_b16_d16_hi v163, v167 offset:9216
	s_waitcnt vmcnt(1) lgkmcnt(15)
	v_mul_f32_e32 v208, v212, v208
	v_bfe_u32 v206, v208, 16, 1
	v_add3_u32 v208, v208, v206, s52
	ds_write_b16_d16_hi v205, v208
	s_waitcnt vmcnt(0)
	v_mul_f32_e32 v213, 0x3e000000, v213
	v_bfe_u32 v206, v213, 16, 1
	v_add3_u32 v213, v213, v206, s52
	ds_write_b16_d16_hi v205, v213 offset:18432
	v_mul_f32_e32 v209, v212, v209
	v_bfe_u32 v206, v209, 16, 1
	v_add3_u32 v209, v209, v206, s52
	ds_write_b16_d16_hi v205, v209 offset:9216

.LBB0_376:
	s_or_b64 exec, exec, s[0:1]
	v_readlane_b32 s56, v250, 0
	v_readlane_b32 s57, v250, 1
	v_readlane_b32 s62, v250, 6
	v_readlane_b32 s63, v250, 7
	v_bfe_u32 v12, v8, 4, 2
	v_ashrrev_i32_e32 v13, 7, v8
	s_mov_b64 s[44:45], s[56:57]
	s_mov_b64 s[50:51], s[62:63]
	s_movk_i32 s0, 0x80
	v_bfe_u32 v17, v8, 6, 1
	v_lshlrev_b32_e32 v14, 4, v12
	v_mov_b32_e32 v9, s51
	v_mov_b32_e32 v10, s45
	v_cmp_gt_u32_e64 s[2:3], s0, v8
	v_lshlrev_b32_e32 v18, 12, v12
	v_lshlrev_b32_e32 v12, 1, v13
	v_and_b32_e32 v16, 15, v8
	v_and_b32_e32 v1, 0x7fffffc0, v8
	v_cndmask_b32_e64 v9, v9, v10, s[2:3]
	v_mov_b32_e32 v8, s50
	v_mov_b32_e32 v10, s44
	v_add3_u32 v12, s28, v12, v17
	s_lshl_b32 s0, s16, 14
	v_cndmask_b32_e64 v8, v8, v10, s[2:3]
	v_lshlrev_b32_e32 v15, 9, v17
	v_lshlrev_b32_e32 v10, 8, v13
	v_ashrrev_i32_e32 v13, 31, v12
	s_add_i32 s0, s0, 0xff400000
	v_mul_u32_u24_e32 v0, 0x210, v16
	v_lshlrev_b32_e32 v1, 1, v1
	v_lshlrev_b64 v[12:13], 15, v[12:13]
	v_lshlrev_b32_e32 v19, 7, v16
	v_or3_b32 v148, s0, v18, v15
	v_add3_u32 v4, v0, v1, v14
	v_ashrrev_i32_e32 v11, 31, v10
	v_or3_b32 v12, v12, v19, v14
	v_lshlrev_b64 v[14:15], 2, v[148:149]
	s_waitcnt lgkmcnt(0)
	s_barrier
	ds_read_b128 v[0:3], v4
	ds_read_b128 v[4:7], v4 offset:64
	v_lshl_add_u64 v[10:11], v[10:11], 2, v[14:15]
	v_lshlrev_b32_e32 v148, 2, v16
	v_lshl_add_u64 v[14:15], v[10:11], 0, v[148:149]
	v_lshl_add_u32 v10, v17, 8, s10
	v_ashrrev_i32_e32 v11, 31, v10
	v_lshl_add_u64 v[10:11], v[10:11], 2, v[148:149]
	v_lshl_add_u64 v[16:17], v[8:9], 0, v[10:11]
	s_mov_b64 s[0:1], 0
	s_mov_b32 s44, 0xc1000000
	v_readlane_b32 s58, v250, 2
	v_readlane_b32 s59, v250, 3
	v_readlane_b32 s60, v250, 4
	v_readlane_b32 s61, v250, 5
	v_readlane_b32 s64, v250, 8
	v_readlane_b32 s65, v250, 9
	v_readlane_b32 s66, v250, 10
	v_readlane_b32 s67, v250, 11
	v_readlane_b32 s68, v250, 12
	v_readlane_b32 s69, v250, 13
	v_readlane_b32 s70, v250, 14
	v_readlane_b32 s71, v250, 15
	v_lshl_add_u64 v[168:169], s[82:83], 0, v[12:13]
	v_add_co_u32_e32 v168, vcc, 0x1fc3a000, v168
	s_nop 1
	v_addc_co_u32_e32 v169, vcc, 0, v169, vcc
	v_add_co_u32_e32 v170, vcc, 0x1000, v168
	s_nop 1
	v_addc_co_u32_e32 v171, vcc, 0, v169, vcc
	v_lshl_add_u64 v[204:205], v[16:17], 0, s[0:1]
	global_load_dwordx4 v[88:91], v[168:169], off offset:256
	global_load_dwordx4 v[92:95], v[168:169], off offset:320
	global_load_dwordx4 v[96:99], v[168:169], off offset:2304
	global_load_dwordx4 v[100:103], v[168:169], off offset:2368
	global_load_dwordx4 v[104:107], v[170:171], off offset:256
	global_load_dwordx4 v[108:111], v[170:171], off offset:320
	global_load_dwordx4 v[112:115], v[170:171], off offset:2304
	global_load_dwordx4 v[116:119], v[170:171], off offset:2368
	global_load_dword v120, v[204:205], off
	global_load_dword v121, v[204:205], off offset:64
	global_load_dword v122, v[204:205], off offset:128
	global_load_dword v123, v[204:205], off offset:192
	s_waitcnt vmcnt(0)
.LBB0_377:
	s_cmpk_eq_i32 s0, 0x300
	s_cbranch_scc1 .Llora_nopf
	v_lshl_add_u64 v[168:169], s[82:83], 0, v[12:13]
	v_add_co_u32_e32 v168, vcc, 0x1fc3c000, v168
	s_nop 1
	v_addc_co_u32_e32 v169, vcc, 0, v169, vcc
	v_add_co_u32_e32 v170, vcc, 0x1000, v168
	s_nop 1
	v_addc_co_u32_e32 v171, vcc, 0, v169, vcc
	v_lshl_add_u64 v[204:205], v[16:17], 0, s[0:1]
	global_load_dwordx4 v[124:127], v[168:169], off offset:256
	global_load_dwordx4 v[128:131], v[168:169], off offset:320
	global_load_dwordx4 v[132:135], v[168:169], off offset:2304
	global_load_dwordx4 v[136:139], v[168:169], off offset:2368
	global_load_dwordx4 v[140:143], v[170:171], off offset:256
	global_load_dwordx4 v[152:155], v[170:171], off offset:320
	global_load_dwordx4 v[156:159], v[170:171], off offset:2304
	global_load_dwordx4 v[160:163], v[170:171], off offset:2368
	global_load_dword v164, v[204:205], off offset:256
	global_load_dword v165, v[204:205], off offset:320
	global_load_dword v166, v[204:205], off offset:384
	global_load_dword v167, v[204:205], off offset:448
.Llora_nopf:
	v_lshl_add_u64 v[28:29], s[82:83], 0, v[12:13]
	v_add_co_u32_e32 v30, vcc, 0x1fc3a000, v28
	v_lshl_add_u64 v[26:27], s[82:83], 0, v[14:15]
	s_nop 0
	v_addc_co_u32_e32 v31, vcc, 0, v29, vcc
	s_waitcnt lgkmcnt(1)
	v_mfma_f32_16x16x32_bf16 v[8:11], v[0:3], v[88:91], 0
	s_waitcnt lgkmcnt(0)
	v_mfma_f32_16x16x32_bf16 v[8:11], v[4:7], v[92:95], v[8:11]
	s_nop 7
	v_lshl_add_u64 v[18:19], v[16:17], 0, s[0:1]
	s_add_u32 s0, s0, 0x100
	s_addc_u32 s1, s1, 0
	s_cmpk_eq_i32 s0, 0x400
	s_nop 1
	v_add_f32_e32 v8, v120, v8
	v_mul_f32_e32 v8, 0xbfb8aa3b, v8
	v_exp_f32_e32 v8, v8
	s_nop 0
	v_add_f32_e32 v8, 1.0, v8
	v_div_scale_f32 v20, s[4:5], v8, v8, 1.0
	v_rcp_f32_e32 v21, v20
	s_mov_b32 s4, 0x124a4000
	v_fma_f32 v22, -v20, v21, 1.0
	v_fmac_f32_e32 v21, v22, v21
	v_div_scale_f32 v22, vcc, 1.0, v8, 1.0
	v_mul_f32_e32 v23, v22, v21
	v_fma_f32 v24, -v20, v23, v22
	v_fmac_f32_e32 v23, v24, v21
	v_fma_f32 v20, -v20, v23, v22
	v_div_fmas_f32 v20, v20, v21, v23
	v_div_fixup_f32 v8, v20, v8, 1.0
	v_mul_f32_e32 v20, 0xbf1b4598, v8
	v_mul_f32_e32 v20, 0x3fb8aa3b, v20
	v_exp_f32_e32 v20, v20
	v_add_co_u32_e32 v22, vcc, s4, v26
	s_mov_b32 s4, 0x124a5000
	s_nop 0
	v_addc_co_u32_e32 v23, vcc, 0, v27, vcc
	v_cndmask_b32_e64 v8, v8, v20, s[2:3]
	v_add_co_u32_e32 v20, vcc, s4, v26
	s_nop 1
	v_addc_co_u32_e32 v21, vcc, 0, v27, vcc
	global_store_dword v[20:21], v8, off offset:-4096
	v_add_f32_e32 v8, v120, v9
	v_mul_f32_e32 v8, 0xbfb8aa3b, v8
	v_exp_f32_e32 v8, v8
	s_nop 0
	v_add_f32_e32 v8, 1.0, v8
	v_div_scale_f32 v9, s[4:5], v8, v8, 1.0
	v_rcp_f32_e32 v24, v9
	s_nop 0
	v_fma_f32 v25, -v9, v24, 1.0
	v_fmac_f32_e32 v24, v25, v24
	v_div_scale_f32 v25, vcc, 1.0, v8, 1.0
	v_mul_f32_e32 v33, v25, v24
	v_fma_f32 v34, -v9, v33, v25
	v_fmac_f32_e32 v33, v34, v24
	v_fma_f32 v9, -v9, v33, v25
	v_div_fmas_f32 v9, v9, v24, v33
	v_div_fixup_f32 v8, v9, v8, 1.0
	v_mul_f32_e32 v9, 0xbf1b4598, v8
	v_mul_f32_e32 v9, 0x3fb8aa3b, v9
	v_exp_f32_e32 v9, v9
	s_nop 0
	v_cndmask_b32_e64 v8, v8, v9, s[2:3]
	global_store_dword v[20:21], v8, off
	v_add_f32_e32 v8, v120, v10
	v_mul_f32_e32 v8, 0xbfb8aa3b, v8
	v_exp_f32_e32 v8, v8
	s_nop 0
	v_add_f32_e32 v8, 1.0, v8
	v_div_scale_f32 v9, s[4:5], v8, v8, 1.0
	v_rcp_f32_e32 v10, v9
	s_mov_b32 s4, 0x124a6000
	v_fma_f32 v24, -v9, v10, 1.0
	v_fmac_f32_e32 v10, v24, v10
	v_div_scale_f32 v24, vcc, 1.0, v8, 1.0
	v_mul_f32_e32 v25, v24, v10
	v_fma_f32 v33, -v9, v25, v24
	v_fmac_f32_e32 v25, v33, v10
	v_fma_f32 v9, -v9, v25, v24
	v_div_fmas_f32 v9, v9, v10, v25
	v_div_fixup_f32 v8, v9, v8, 1.0
	v_mul_f32_e32 v9, 0xbf1b4598, v8
	v_mul_f32_e32 v9, 0x3fb8aa3b, v9
	v_exp_f32_e32 v9, v9
	v_add_co_u32_e32 v24, vcc, s4, v26
	s_mov_b32 s4, 0x124a7000
	s_nop 0
	v_addc_co_u32_e32 v25, vcc, 0, v27, vcc
	v_add_co_u32_e32 v26, vcc, s4, v26
	v_cndmask_b32_e64 v8, v8, v9, s[2:3]
	s_nop 0
	v_addc_co_u32_e32 v27, vcc, 0, v27, vcc
	global_store_dword v[26:27], v8, off offset:-4096
	v_add_f32_e32 v8, v120, v11
	v_mul_f32_e32 v8, 0xbfb8aa3b, v8
	v_exp_f32_e32 v8, v8
	s_nop 0
	v_add_f32_e32 v8, 1.0, v8
	v_div_scale_f32 v9, s[4:5], v8, v8, 1.0
	v_rcp_f32_e32 v10, v9
	s_nop 0
	v_fma_f32 v11, -v9, v10, 1.0
	v_fmac_f32_e32 v10, v11, v10
	v_div_scale_f32 v11, vcc, 1.0, v8, 1.0
	v_mul_f32_e32 v32, v11, v10
	v_fma_f32 v33, -v9, v32, v11
	v_fmac_f32_e32 v32, v33, v10
	v_fma_f32 v9, -v9, v32, v11
	v_div_fmas_f32 v9, v9, v10, v32
	v_div_fixup_f32 v8, v9, v8, 1.0
	v_mul_f32_e32 v9, 0xbf1b4598, v8
	v_mul_f32_e32 v9, 0x3fb8aa3b, v9
	v_exp_f32_e32 v9, v9
	s_nop 0
	v_cndmask_b32_e64 v8, v8, v9, s[2:3]
	global_store_dword v[26:27], v8, off
	s_nop 0
	v_mfma_f32_16x16x32_bf16 v[8:11], v[0:3], v[96:99], 0
	v_mfma_f32_16x16x32_bf16 v[8:11], v[4:7], v[100:103], v[8:11]
	s_nop 7
	s_nop 5
	v_add_f32_e32 v8, v121, v8
	v_mul_f32_e32 v8, 0xbfb8aa3b, v8
	v_exp_f32_e32 v8, v8
	s_nop 0
	v_add_f32_e32 v8, 1.0, v8
	v_div_scale_f32 v31, s[4:5], v8, v8, 1.0
	v_rcp_f32_e32 v32, v31
	s_nop 0
	v_fma_f32 v33, -v31, v32, 1.0
	v_fmac_f32_e32 v32, v33, v32
	v_div_scale_f32 v33, vcc, 1.0, v8, 1.0
	v_mul_f32_e32 v34, v33, v32
	v_fma_f32 v35, -v31, v34, v33
	v_fmac_f32_e32 v34, v35, v32
	v_fma_f32 v31, -v31, v34, v33
	v_div_fmas_f32 v31, v31, v32, v34
	v_div_fixup_f32 v8, v31, v8, 1.0
	v_mul_f32_e32 v31, 0xbf1b4598, v8
	v_mul_f32_e32 v31, 0x3fb8aa3b, v31
	v_exp_f32_e32 v31, v31
	s_nop 0
	v_cndmask_b32_e64 v8, v8, v31, s[2:3]
	global_store_dword v[22:23], v8, off offset:64
	v_add_f32_e32 v8, v121, v9
	v_mul_f32_e32 v8, 0xbfb8aa3b, v8
	v_exp_f32_e32 v8, v8
	s_nop 0
	v_add_f32_e32 v8, 1.0, v8
	v_div_scale_f32 v9, s[4:5], v8, v8, 1.0
	v_rcp_f32_e32 v31, v9
	s_nop 0
	v_fma_f32 v32, -v9, v31, 1.0
	v_fmac_f32_e32 v31, v32, v31
	v_div_scale_f32 v32, vcc, 1.0, v8, 1.0
	v_mul_f32_e32 v33, v32, v31
	v_fma_f32 v34, -v9, v33, v32
	v_fmac_f32_e32 v33, v34, v31
	v_fma_f32 v9, -v9, v33, v32
	v_div_fmas_f32 v9, v9, v31, v33
	v_div_fixup_f32 v8, v9, v8, 1.0
	v_mul_f32_e32 v9, 0xbf1b4598, v8
	v_mul_f32_e32 v9, 0x3fb8aa3b, v9
	v_exp_f32_e32 v9, v9
	s_nop 0
	v_cndmask_b32_e64 v8, v8, v9, s[2:3]
	global_store_dword v[20:21], v8, off offset:64
	v_add_f32_e32 v8, v121, v10
	v_mul_f32_e32 v8, 0xbfb8aa3b, v8
	v_exp_f32_e32 v8, v8
	s_nop 0
	v_add_f32_e32 v8, 1.0, v8
	v_div_scale_f32 v9, s[4:5], v8, v8, 1.0
	v_rcp_f32_e32 v10, v9
	s_nop 0
	v_fma_f32 v31, -v9, v10, 1.0
	v_fmac_f32_e32 v10, v31, v10
	v_div_scale_f32 v31, vcc, 1.0, v8, 1.0
	v_mul_f32_e32 v32, v31, v10
	v_fma_f32 v33, -v9, v32, v31
	v_fmac_f32_e32 v32, v33, v10
	v_fma_f32 v9, -v9, v32, v31
	v_div_fmas_f32 v9, v9, v10, v32
	v_div_fixup_f32 v8, v9, v8, 1.0
	v_mul_f32_e32 v9, 0xbf1b4598, v8
	v_mul_f32_e32 v9, 0x3fb8aa3b, v9
	v_exp_f32_e32 v9, v9
	s_nop 0
	v_cndmask_b32_e64 v8, v8, v9, s[2:3]
	global_store_dword v[24:25], v8, off offset:64
	v_add_f32_e32 v8, v121, v11
	v_mul_f32_e32 v8, 0xbfb8aa3b, v8
	v_exp_f32_e32 v8, v8
	s_nop 0
	v_add_f32_e32 v8, 1.0, v8
	v_div_scale_f32 v9, s[4:5], v8, v8, 1.0
	v_rcp_f32_e32 v10, v9
	s_mov_b32 s4, 0x1fc3b000
	v_fma_f32 v11, -v9, v10, 1.0
	v_fmac_f32_e32 v10, v11, v10
	v_div_scale_f32 v11, vcc, 1.0, v8, 1.0
	v_mul_f32_e32 v30, v11, v10
	v_fma_f32 v31, -v9, v30, v11
	v_fmac_f32_e32 v30, v31, v10
	v_fma_f32 v9, -v9, v30, v11
	v_div_fmas_f32 v9, v9, v10, v30
	v_div_fixup_f32 v8, v9, v8, 1.0
	v_mul_f32_e32 v9, 0xbf1b4598, v8
	v_mul_f32_e32 v9, 0x3fb8aa3b, v9
	v_exp_f32_e32 v9, v9
	v_add_co_u32_e32 v28, vcc, s4, v28
	v_cndmask_b32_e64 v8, v8, v9, s[2:3]
	global_store_dword v[26:27], v8, off offset:64
	v_addc_co_u32_e32 v29, vcc, 0, v29, vcc
	v_mfma_f32_16x16x32_bf16 v[8:11], v[0:3], v[104:107], 0
	v_mfma_f32_16x16x32_bf16 v[8:11], v[4:7], v[108:111], v[8:11]
	s_nop 7
	s_nop 5
	v_add_f32_e32 v8, v122, v8
	v_mul_f32_e32 v8, 0xbfb8aa3b, v8
	v_exp_f32_e32 v8, v8
	s_nop 0
	v_add_f32_e32 v8, 1.0, v8
	v_div_scale_f32 v31, s[4:5], v8, v8, 1.0
	v_rcp_f32_e32 v32, v31
	s_nop 0
	v_fma_f32 v33, -v31, v32, 1.0
	v_fmac_f32_e32 v32, v33, v32
	v_div_scale_f32 v33, vcc, 1.0, v8, 1.0
	v_mul_f32_e32 v34, v33, v32
	v_fma_f32 v35, -v31, v34, v33
	v_fmac_f32_e32 v34, v35, v32
	v_fma_f32 v31, -v31, v34, v33
	v_div_fmas_f32 v31, v31, v32, v34
	v_div_fixup_f32 v8, v31, v8, 1.0
	v_mul_f32_e32 v31, 0xbf1b4598, v8
	v_mul_f32_e32 v31, 0x3fb8aa3b, v31
	v_exp_f32_e32 v31, v31
	s_nop 0
	v_cndmask_b32_e64 v8, v8, v31, s[2:3]
	global_store_dword v[22:23], v8, off offset:128
	v_add_f32_e32 v8, v122, v9
	v_mul_f32_e32 v8, 0xbfb8aa3b, v8
	v_exp_f32_e32 v8, v8
	s_nop 0
	v_add_f32_e32 v8, 1.0, v8
	v_div_scale_f32 v9, s[4:5], v8, v8, 1.0
	v_rcp_f32_e32 v31, v9
	s_nop 0
	v_fma_f32 v32, -v9, v31, 1.0
	v_fmac_f32_e32 v31, v32, v31
	v_div_scale_f32 v32, vcc, 1.0, v8, 1.0
	v_mul_f32_e32 v33, v32, v31
	v_fma_f32 v34, -v9, v33, v32
	v_fmac_f32_e32 v33, v34, v31
	v_fma_f32 v9, -v9, v33, v32
	v_div_fmas_f32 v9, v9, v31, v33
	v_div_fixup_f32 v8, v9, v8, 1.0
	v_mul_f32_e32 v9, 0xbf1b4598, v8
	v_mul_f32_e32 v9, 0x3fb8aa3b, v9
	v_exp_f32_e32 v9, v9
	s_nop 0
	v_cndmask_b32_e64 v8, v8, v9, s[2:3]
	global_store_dword v[20:21], v8, off offset:128
	v_add_f32_e32 v8, v122, v10
	v_mul_f32_e32 v8, 0xbfb8aa3b, v8
	v_exp_f32_e32 v8, v8
	s_nop 0
	v_add_f32_e32 v8, 1.0, v8
	v_div_scale_f32 v9, s[4:5], v8, v8, 1.0
	v_rcp_f32_e32 v10, v9
	s_nop 0
	v_fma_f32 v31, -v9, v10, 1.0
	v_fmac_f32_e32 v10, v31, v10
	v_div_scale_f32 v31, vcc, 1.0, v8, 1.0
	v_mul_f32_e32 v32, v31, v10
	v_fma_f32 v33, -v9, v32, v31
	v_fmac_f32_e32 v32, v33, v10
	v_fma_f32 v9, -v9, v32, v31
	v_div_fmas_f32 v9, v9, v10, v32
	v_div_fixup_f32 v8, v9, v8, 1.0
	v_mul_f32_e32 v9, 0xbf1b4598, v8
	v_mul_f32_e32 v9, 0x3fb8aa3b, v9
	v_exp_f32_e32 v9, v9
	s_nop 0
	v_cndmask_b32_e64 v8, v8, v9, s[2:3]
	global_store_dword v[24:25], v8, off offset:128
	v_add_f32_e32 v8, v122, v11
	v_mul_f32_e32 v8, 0xbfb8aa3b, v8
	v_exp_f32_e32 v8, v8
	s_nop 0
	v_add_f32_e32 v8, 1.0, v8
	v_div_scale_f32 v9, s[4:5], v8, v8, 1.0
	v_rcp_f32_e32 v10, v9
	s_nop 0
	v_fma_f32 v11, -v9, v10, 1.0
	v_fmac_f32_e32 v10, v11, v10
	v_div_scale_f32 v11, vcc, 1.0, v8, 1.0
	v_mul_f32_e32 v30, v11, v10
	v_fma_f32 v31, -v9, v30, v11
	v_fmac_f32_e32 v30, v31, v10
	v_fma_f32 v9, -v9, v30, v11
	v_div_fmas_f32 v9, v9, v10, v30
	v_div_fixup_f32 v8, v9, v8, 1.0
	v_mul_f32_e32 v9, 0xbf1b4598, v8
	v_mul_f32_e32 v9, 0x3fb8aa3b, v9
	v_exp_f32_e32 v9, v9
	s_nop 0
	v_cndmask_b32_e64 v8, v8, v9, s[2:3]
	global_store_dword v[26:27], v8, off offset:128
	s_nop 0
	v_mfma_f32_16x16x32_bf16 v[8:11], v[0:3], v[112:115], 0
	v_mfma_f32_16x16x32_bf16 v[8:11], v[4:7], v[116:119], v[8:11]
	s_nop 7
	s_nop 6
	v_add_f32_e32 v8, v123, v8
	v_mul_f32_e32 v8, 0xbfb8aa3b, v8
	v_exp_f32_e32 v8, v8
	s_nop 0
	v_add_f32_e32 v8, 1.0, v8
	v_div_scale_f32 v19, s[4:5], v8, v8, 1.0
	v_rcp_f32_e32 v28, v19
	s_nop 0
	v_fma_f32 v29, -v19, v28, 1.0
	v_fmac_f32_e32 v28, v29, v28
	v_div_scale_f32 v29, vcc, 1.0, v8, 1.0
	v_mul_f32_e32 v30, v29, v28
	v_fma_f32 v31, -v19, v30, v29
	v_fmac_f32_e32 v30, v31, v28
	v_fma_f32 v19, -v19, v30, v29
	v_div_fmas_f32 v19, v19, v28, v30
	v_div_fixup_f32 v8, v19, v8, 1.0
	v_mul_f32_e32 v19, 0xbf1b4598, v8
	v_mul_f32_e32 v19, 0x3fb8aa3b, v19
	v_exp_f32_e32 v19, v19
	s_nop 0
	v_cndmask_b32_e64 v8, v8, v19, s[2:3]
	global_store_dword v[22:23], v8, off offset:192
	v_add_f32_e32 v8, v123, v9
	v_mul_f32_e32 v8, 0xbfb8aa3b, v8
	v_exp_f32_e32 v8, v8
	s_nop 0
	v_add_f32_e32 v8, 1.0, v8
	v_div_scale_f32 v9, s[4:5], v8, v8, 1.0
	v_rcp_f32_e32 v19, v9
	s_nop 0
	v_fma_f32 v22, -v9, v19, 1.0
	v_fmac_f32_e32 v19, v22, v19
	v_div_scale_f32 v22, vcc, 1.0, v8, 1.0
	v_mul_f32_e32 v23, v22, v19
	v_fma_f32 v28, -v9, v23, v22
	v_fmac_f32_e32 v23, v28, v19
	v_fma_f32 v9, -v9, v23, v22
	v_div_fmas_f32 v9, v9, v19, v23
	v_div_fixup_f32 v8, v9, v8, 1.0
	v_mul_f32_e32 v9, 0xbf1b4598, v8
	v_mul_f32_e32 v9, 0x3fb8aa3b, v9
	v_exp_f32_e32 v9, v9
	s_nop 0
	v_cndmask_b32_e64 v8, v8, v9, s[2:3]
	global_store_dword v[20:21], v8, off offset:192
	v_add_f32_e32 v8, v123, v10
	v_mul_f32_e32 v8, 0xbfb8aa3b, v8
	v_exp_f32_e32 v8, v8
	s_nop 0
	v_add_f32_e32 v8, 1.0, v8
	v_div_scale_f32 v9, s[4:5], v8, v8, 1.0
	v_rcp_f32_e32 v10, v9
	s_nop 0
	v_fma_f32 v19, -v9, v10, 1.0
	v_fmac_f32_e32 v10, v19, v10
	v_div_scale_f32 v19, vcc, 1.0, v8, 1.0
	v_mul_f32_e32 v20, v19, v10
	v_fma_f32 v21, -v9, v20, v19
	v_fmac_f32_e32 v20, v21, v10
	v_fma_f32 v9, -v9, v20, v19
	v_div_fmas_f32 v9, v9, v10, v20
	v_div_fixup_f32 v8, v9, v8, 1.0
	v_mul_f32_e32 v9, 0xbf1b4598, v8
	v_mul_f32_e32 v9, 0x3fb8aa3b, v9
	v_exp_f32_e32 v9, v9
	s_nop 0
	v_cndmask_b32_e64 v8, v8, v9, s[2:3]
	global_store_dword v[24:25], v8, off offset:192
	v_add_f32_e32 v8, v123, v11
	v_mul_f32_e32 v8, 0xbfb8aa3b, v8
	v_exp_f32_e32 v8, v8
	s_nop 0
	v_add_f32_e32 v8, 1.0, v8
	v_div_scale_f32 v9, s[4:5], v8, v8, 1.0
	v_rcp_f32_e32 v10, v9
	s_mov_b64 s[4:5], 0x2000
	v_lshl_add_u64 v[12:13], v[12:13], 0, s[4:5]
	s_mov_b64 s[4:5], 0x100
	v_fma_f32 v11, -v9, v10, 1.0
	v_fmac_f32_e32 v10, v11, v10
	v_div_scale_f32 v11, vcc, 1.0, v8, 1.0
	v_mul_f32_e32 v18, v11, v10
	v_fma_f32 v19, -v9, v18, v11
	v_fmac_f32_e32 v18, v19, v10
	v_fma_f32 v9, -v9, v18, v11
	v_div_fmas_f32 v9, v9, v10, v18
	v_div_fixup_f32 v8, v9, v8, 1.0
	v_mul_f32_e32 v9, 0xbf1b4598, v8
	v_mul_f32_e32 v9, 0x3fb8aa3b, v9
	v_exp_f32_e32 v9, v9
	v_lshl_add_u64 v[14:15], v[14:15], 0, s[4:5]
	v_cndmask_b32_e64 v8, v8, v9, s[2:3]
	global_store_dword v[26:27], v8, off offset:192
	s_cbranch_scc1 .Llora_done
	s_waitcnt vmcnt(16)
	v_mov_b32_e32 v88, v124
	v_mov_b32_e32 v89, v125
	v_mov_b32_e32 v90, v126
	v_mov_b32_e32 v91, v127
	v_mov_b32_e32 v92, v128
	v_mov_b32_e32 v93, v129
	v_mov_b32_e32 v94, v130
	v_mov_b32_e32 v95, v131
	v_mov_b32_e32 v96, v132
	v_mov_b32_e32 v97, v133
	v_mov_b32_e32 v98, v134
	v_mov_b32_e32 v99, v135
	v_mov_b32_e32 v100, v136
	v_mov_b32_e32 v101, v137
	v_mov_b32_e32 v102, v138
	v_mov_b32_e32 v103, v139
	v_mov_b32_e32 v104, v140
	v_mov_b32_e32 v105, v141
	v_mov_b32_e32 v106, v142
	v_mov_b32_e32 v107, v143
	v_mov_b32_e32 v108, v152
	v_mov_b32_e32 v109, v153
	v_mov_b32_e32 v110, v154
	v_mov_b32_e32 v111, v155
	v_mov_b32_e32 v112, v156
	v_mov_b32_e32 v113, v157
	v_mov_b32_e32 v114, v158
	v_mov_b32_e32 v115, v159
	v_mov_b32_e32 v116, v160
	v_mov_b32_e32 v117, v161
	v_mov_b32_e32 v118, v162
	v_mov_b32_e32 v119, v163
	v_mov_b32_e32 v120, v164
	v_mov_b32_e32 v121, v165
	v_mov_b32_e32 v122, v166
	v_mov_b32_e32 v123, v167
	s_branch .LBB0_377
.Llora_done:
.LBB0_378:
	s_mov_b64 s[0:1], 0

.LBB0_502:
	s_mov_b32 s11, s21
	v_mov_b32_e32 v88, v3
	v_ashrrev_i32_e32 v89, 6, v88
	v_lshlrev_b32_e32 v90, 2, v89
	ds_read_b32 v91, v90 offset:28672
	ds_read2st64_b32 v[92:93], v90 offset0:110 offset1:111
	ds_read2st64_b32 v[94:95], v90 offset0:108 offset1:109
	v_add_lshl_u32 v89, v89, v2, 1
	v_add_u32_e32 v100, 0x100, v3
	v_ashrrev_i32_e32 v101, 6, v100
	v_lshlrev_b32_e32 v102, 2, v101
	ds_read_b32 v103, v102 offset:28672
	ds_read2st64_b32 v[104:105], v102 offset0:110 offset1:111
	ds_read2st64_b32 v[106:107], v102 offset0:108 offset1:109
	v_add_lshl_u32 v101, v101, v2, 1
	v_add_u32_e32 v112, 0x200, v3
	v_ashrrev_i32_e32 v113, 6, v112
	v_lshlrev_b32_e32 v114, 2, v113
	ds_read_b32 v115, v114 offset:28672
	ds_read2st64_b32 v[116:117], v114 offset0:110 offset1:111
	ds_read2st64_b32 v[118:119], v114 offset0:108 offset1:109
	v_add_lshl_u32 v113, v113, v2, 1
	v_add_u32_e32 v124, 0x300, v3
	v_ashrrev_i32_e32 v125, 6, v124
	v_lshlrev_b32_e32 v126, 2, v125
	ds_read_b32 v127, v126 offset:28672
	ds_read2st64_b32 v[128:129], v126 offset0:110 offset1:111
	ds_read2st64_b32 v[130:131], v126 offset0:108 offset1:109
	v_add_lshl_u32 v125, v125, v2, 1
	s_waitcnt lgkmcnt(11)
	v_mov_b32_e32 v96, v91
	v_ashrrev_i32_e32 v97, 31, v91
	v_lshlrev_b64 v[96:97], 11, v[96:97]
	v_lshl_add_u64 v[96:97], s[12:13], 0, v[96:97]
	v_lshl_add_u64 v[98:99], v[96:97], 0, s[20:21]
	v_lshl_add_u64 v[98:99], v[98:99], 0, v[148:149]
	global_load_dword v90, v[98:99], off
	v_lshl_add_u64 v[96:97], v[96:97], 0, s[10:11]
	v_lshl_add_u64 v[96:97], v[96:97], 0, v[148:149]
	global_load_dword v91, v[96:97], off offset:1024
	s_waitcnt lgkmcnt(9)
	v_sub_f32_e32 v94, v32, v94
	v_mul_f32_e32 v94, 0x3fb8aa3b, v94
	v_exp_f32_e32 v94, v94
	v_sub_f32_e32 v95, v33, v95
	v_mul_f32_e32 v95, 0x3fb8aa3b, v95
	v_exp_f32_e32 v95, v95
	v_mul_f32_e32 v92, v92, v94
	v_mul_f32_e32 v93, v93, v95
	s_waitcnt lgkmcnt(8)
	v_mov_b32_e32 v108, v103
	v_ashrrev_i32_e32 v109, 31, v103
	v_lshlrev_b64 v[108:109], 11, v[108:109]
	v_lshl_add_u64 v[108:109], s[12:13], 0, v[108:109]
	v_lshl_add_u64 v[110:111], v[108:109], 0, s[20:21]
	v_lshl_add_u64 v[110:111], v[110:111], 0, v[148:149]
	global_load_dword v102, v[110:111], off
	v_lshl_add_u64 v[108:109], v[108:109], 0, s[10:11]
	v_lshl_add_u64 v[108:109], v[108:109], 0, v[148:149]
	global_load_dword v103, v[108:109], off offset:1024
	s_waitcnt lgkmcnt(6)
	v_sub_f32_e32 v106, v32, v106
	v_mul_f32_e32 v106, 0x3fb8aa3b, v106
	v_exp_f32_e32 v106, v106
	v_sub_f32_e32 v107, v33, v107
	v_mul_f32_e32 v107, 0x3fb8aa3b, v107
	v_exp_f32_e32 v107, v107
	v_mul_f32_e32 v104, v104, v106
	v_mul_f32_e32 v105, v105, v107
	s_waitcnt lgkmcnt(5)
	v_mov_b32_e32 v120, v115
	v_ashrrev_i32_e32 v121, 31, v115
	v_lshlrev_b64 v[120:121], 11, v[120:121]
	v_lshl_add_u64 v[120:121], s[12:13], 0, v[120:121]
	v_lshl_add_u64 v[122:123], v[120:121], 0, s[20:21]
	v_lshl_add_u64 v[122:123], v[122:123], 0, v[148:149]
	global_load_dword v114, v[122:123], off
	v_lshl_add_u64 v[120:121], v[120:121], 0, s[10:11]
	v_lshl_add_u64 v[120:121], v[120:121], 0, v[148:149]
	global_load_dword v115, v[120:121], off offset:1024
	s_waitcnt lgkmcnt(3)
	v_sub_f32_e32 v118, v32, v118
	v_mul_f32_e32 v118, 0x3fb8aa3b, v118
	v_exp_f32_e32 v118, v118
	v_sub_f32_e32 v119, v33, v119
	v_mul_f32_e32 v119, 0x3fb8aa3b, v119
	v_exp_f32_e32 v119, v119
	v_mul_f32_e32 v116, v116, v118
	v_mul_f32_e32 v117, v117, v119
	s_waitcnt lgkmcnt(2)
	v_mov_b32_e32 v132, v127
	v_ashrrev_i32_e32 v133, 31, v127
	v_lshlrev_b64 v[132:133], 11, v[132:133]
	v_lshl_add_u64 v[132:133], s[12:13], 0, v[132:133]
	v_lshl_add_u64 v[134:135], v[132:133], 0, s[20:21]
	v_lshl_add_u64 v[134:135], v[134:135], 0, v[148:149]
	global_load_dword v126, v[134:135], off
	v_lshl_add_u64 v[132:133], v[132:133], 0, s[10:11]
	v_lshl_add_u64 v[132:133], v[132:133], 0, v[148:149]
	global_load_dword v127, v[132:133], off offset:1024
	s_waitcnt lgkmcnt(0)
	v_sub_f32_e32 v130, v32, v130
	v_mul_f32_e32 v130, 0x3fb8aa3b, v130
	v_exp_f32_e32 v130, v130
	v_sub_f32_e32 v131, v33, v131
	v_mul_f32_e32 v131, 0x3fb8aa3b, v131
	v_exp_f32_e32 v131, v131
	v_mul_f32_e32 v128, v128, v130
	v_mul_f32_e32 v129, v129, v131
	s_waitcnt vmcnt(7)
	v_mul_f32_e32 v92, v90, v92
	v_bfe_u32 v94, v92, 16, 1
	v_add3_u32 v92, v92, v94, s52
	ds_write_b16_d16_hi v89, v92
	s_waitcnt vmcnt(6)
	v_bfe_u32 v94, v91, 16, 1
	v_add3_u32 v91, v91, v94, s52
	ds_write_b16_d16_hi v89, v91 offset:18432
	v_mul_f32_e32 v93, v90, v93
	v_bfe_u32 v94, v93, 16, 1
	v_add3_u32 v93, v93, v94, s52
	ds_write_b16_d16_hi v89, v93 offset:9216
	s_waitcnt vmcnt(5)
	v_mul_f32_e32 v104, v102, v104
	v_bfe_u32 v106, v104, 16, 1
	v_add3_u32 v104, v104, v106, s52
	ds_write_b16_d16_hi v101, v104
	s_waitcnt vmcnt(4)
	v_bfe_u32 v106, v103, 16, 1
	v_add3_u32 v103, v103, v106, s52
	ds_write_b16_d16_hi v101, v103 offset:18432
	v_mul_f32_e32 v105, v102, v105
	v_bfe_u32 v106, v105, 16, 1
	v_add3_u32 v105, v105, v106, s52
	ds_write_b16_d16_hi v101, v105 offset:9216
	s_waitcnt vmcnt(3)
	v_mul_f32_e32 v116, v114, v116
	v_bfe_u32 v118, v116, 16, 1
	v_add3_u32 v116, v116, v118, s52
	ds_write_b16_d16_hi v113, v116
	s_waitcnt vmcnt(2)
	v_bfe_u32 v118, v115, 16, 1
	v_add3_u32 v115, v115, v118, s52
	ds_write_b16_d16_hi v113, v115 offset:18432
	v_mul_f32_e32 v117, v114, v117
	v_bfe_u32 v118, v117, 16, 1
	v_add3_u32 v117, v117, v118, s52
	ds_write_b16_d16_hi v113, v117 offset:9216
	s_waitcnt vmcnt(1)
	v_mul_f32_e32 v128, v126, v128
	v_bfe_u32 v130, v128, 16, 1
	v_add3_u32 v128, v128, v130, s52
	ds_write_b16_d16_hi v125, v128
	s_waitcnt vmcnt(0)
	v_bfe_u32 v130, v127, 16, 1
	v_add3_u32 v127, v127, v130, s52
	ds_write_b16_d16_hi v125, v127 offset:18432
	v_mul_f32_e32 v129, v126, v129
	v_bfe_u32 v130, v129, 16, 1
	v_add3_u32 v129, v129, v130, s52
	ds_write_b16_d16_hi v125, v129 offset:9216
	v_add_u32_e32 v88, 0x400, v3
	v_ashrrev_i32_e32 v89, 6, v88
	v_lshlrev_b32_e32 v90, 2, v89
	ds_read_b32 v91, v90 offset:28672
	ds_read2st64_b32 v[92:93], v90 offset0:110 offset1:111
	ds_read2st64_b32 v[94:95], v90 offset0:108 offset1:109
	v_add_lshl_u32 v89, v89, v2, 1
	v_add_u32_e32 v100, 0x500, v3
	v_ashrrev_i32_e32 v101, 6, v100
	v_lshlrev_b32_e32 v102, 2, v101
	ds_read_b32 v103, v102 offset:28672
	ds_read2st64_b32 v[104:105], v102 offset0:110 offset1:111
	ds_read2st64_b32 v[106:107], v102 offset0:108 offset1:109
	v_add_lshl_u32 v101, v101, v2, 1
	v_add_u32_e32 v112, 0x600, v3
	v_ashrrev_i32_e32 v113, 6, v112
	v_lshlrev_b32_e32 v114, 2, v113
	ds_read_b32 v115, v114 offset:28672
	ds_read2st64_b32 v[116:117], v114 offset0:110 offset1:111
	ds_read2st64_b32 v[118:119], v114 offset0:108 offset1:109
	v_add_lshl_u32 v113, v113, v2, 1
	v_add_u32_e32 v124, 0x700, v3
	v_ashrrev_i32_e32 v125, 6, v124
	v_lshlrev_b32_e32 v126, 2, v125
	ds_read_b32 v127, v126 offset:28672
	ds_read2st64_b32 v[128:129], v126 offset0:110 offset1:111
	ds_read2st64_b32 v[130:131], v126 offset0:108 offset1:109
	v_add_lshl_u32 v125, v125, v2, 1
	s_waitcnt lgkmcnt(11)
	v_mov_b32_e32 v96, v91
	v_ashrrev_i32_e32 v97, 31, v91
	v_lshlrev_b64 v[96:97], 11, v[96:97]
	v_lshl_add_u64 v[96:97], s[12:13], 0, v[96:97]
	v_lshl_add_u64 v[98:99], v[96:97], 0, s[20:21]
	v_lshl_add_u64 v[98:99], v[98:99], 0, v[148:149]
	global_load_dword v90, v[98:99], off
	v_lshl_add_u64 v[96:97], v[96:97], 0, s[10:11]
	v_lshl_add_u64 v[96:97], v[96:97], 0, v[148:149]
	global_load_dword v91, v[96:97], off offset:1024
	s_waitcnt lgkmcnt(9)
	v_sub_f32_e32 v94, v32, v94
	v_mul_f32_e32 v94, 0x3fb8aa3b, v94
	v_exp_f32_e32 v94, v94
	v_sub_f32_e32 v95, v33, v95
	v_mul_f32_e32 v95, 0x3fb8aa3b, v95
	v_exp_f32_e32 v95, v95
	v_mul_f32_e32 v92, v92, v94
	v_mul_f32_e32 v93, v93, v95
	s_waitcnt lgkmcnt(8)
	v_mov_b32_e32 v108, v103
	v_ashrrev_i32_e32 v109, 31, v103
	v_lshlrev_b64 v[108:109], 11, v[108:109]
	v_lshl_add_u64 v[108:109], s[12:13], 0, v[108:109]
	v_lshl_add_u64 v[110:111], v[108:109], 0, s[20:21]
	v_lshl_add_u64 v[110:111], v[110:111], 0, v[148:149]
	global_load_dword v102, v[110:111], off
	v_lshl_add_u64 v[108:109], v[108:109], 0, s[10:11]
	v_lshl_add_u64 v[108:109], v[108:109], 0, v[148:149]
	global_load_dword v103, v[108:109], off offset:1024
	s_waitcnt lgkmcnt(6)
	v_sub_f32_e32 v106, v32, v106
	v_mul_f32_e32 v106, 0x3fb8aa3b, v106
	v_exp_f32_e32 v106, v106
	v_sub_f32_e32 v107, v33, v107
	v_mul_f32_e32 v107, 0x3fb8aa3b, v107
	v_exp_f32_e32 v107, v107
	v_mul_f32_e32 v104, v104, v106
	v_mul_f32_e32 v105, v105, v107
	s_waitcnt lgkmcnt(5)
	v_mov_b32_e32 v120, v115
	v_ashrrev_i32_e32 v121, 31, v115
	v_lshlrev_b64 v[120:121], 11, v[120:121]
	v_lshl_add_u64 v[120:121], s[12:13], 0, v[120:121]
	v_lshl_add_u64 v[122:123], v[120:121], 0, s[20:21]
	v_lshl_add_u64 v[122:123], v[122:123], 0, v[148:149]
	global_load_dword v114, v[122:123], off
	v_lshl_add_u64 v[120:121], v[120:121], 0, s[10:11]
	v_lshl_add_u64 v[120:121], v[120:121], 0, v[148:149]
	global_load_dword v115, v[120:121], off offset:1024
	s_waitcnt lgkmcnt(3)
	v_sub_f32_e32 v118, v32, v118
	v_mul_f32_e32 v118, 0x3fb8aa3b, v118
	v_exp_f32_e32 v118, v118
	v_sub_f32_e32 v119, v33, v119
	v_mul_f32_e32 v119, 0x3fb8aa3b, v119
	v_exp_f32_e32 v119, v119
	v_mul_f32_e32 v116, v116, v118
	v_mul_f32_e32 v117, v117, v119
	s_waitcnt lgkmcnt(2)
	v_mov_b32_e32 v132, v127
	v_ashrrev_i32_e32 v133, 31, v127
	v_lshlrev_b64 v[132:133], 11, v[132:133]
	v_lshl_add_u64 v[132:133], s[12:13], 0, v[132:133]
	v_lshl_add_u64 v[134:135], v[132:133], 0, s[20:21]
	v_lshl_add_u64 v[134:135], v[134:135], 0, v[148:149]
	global_load_dword v126, v[134:135], off
	v_lshl_add_u64 v[132:133], v[132:133], 0, s[10:11]
	v_lshl_add_u64 v[132:133], v[132:133], 0, v[148:149]
	global_load_dword v127, v[132:133], off offset:1024
	s_waitcnt lgkmcnt(0)
	v_sub_f32_e32 v130, v32, v130
	v_mul_f32_e32 v130, 0x3fb8aa3b, v130
	v_exp_f32_e32 v130, v130
	v_sub_f32_e32 v131, v33, v131
	v_mul_f32_e32 v131, 0x3fb8aa3b, v131
	v_exp_f32_e32 v131, v131
	v_mul_f32_e32 v128, v128, v130
	v_mul_f32_e32 v129, v129, v131
	s_waitcnt vmcnt(7)
	v_mul_f32_e32 v92, v90, v92
	v_bfe_u32 v94, v92, 16, 1
	v_add3_u32 v92, v92, v94, s52
	ds_write_b16_d16_hi v89, v92
	s_waitcnt vmcnt(6)
	v_bfe_u32 v94, v91, 16, 1
	v_add3_u32 v91, v91, v94, s52
	ds_write_b16_d16_hi v89, v91 offset:18432
	v_mul_f32_e32 v93, v90, v93
	v_bfe_u32 v94, v93, 16, 1
	v_add3_u32 v93, v93, v94, s52
	ds_write_b16_d16_hi v89, v93 offset:9216
	s_waitcnt vmcnt(5)
	v_mul_f32_e32 v104, v102, v104
	v_bfe_u32 v106, v104, 16, 1
	v_add3_u32 v104, v104, v106, s52
	ds_write_b16_d16_hi v101, v104
	s_waitcnt vmcnt(4)
	v_bfe_u32 v106, v103, 16, 1
	v_add3_u32 v103, v103, v106, s52
	ds_write_b16_d16_hi v101, v103 offset:18432
	v_mul_f32_e32 v105, v102, v105
	v_bfe_u32 v106, v105, 16, 1
	v_add3_u32 v105, v105, v106, s52
	ds_write_b16_d16_hi v101, v105 offset:9216
	s_waitcnt vmcnt(3)
	v_mul_f32_e32 v116, v114, v116
	v_bfe_u32 v118, v116, 16, 1
	v_add3_u32 v116, v116, v118, s52
	ds_write_b16_d16_hi v113, v116
	s_waitcnt vmcnt(2)
	v_bfe_u32 v118, v115, 16, 1
	v_add3_u32 v115, v115, v118, s52
	ds_write_b16_d16_hi v113, v115 offset:18432
	v_mul_f32_e32 v117, v114, v117
	v_bfe_u32 v118, v117, 16, 1
	v_add3_u32 v117, v117, v118, s52
	ds_write_b16_d16_hi v113, v117 offset:9216
	s_waitcnt vmcnt(1)
	v_mul_f32_e32 v128, v126, v128
	v_bfe_u32 v130, v128, 16, 1
	v_add3_u32 v128, v128, v130, s52
	ds_write_b16_d16_hi v125, v128
	s_waitcnt vmcnt(0)
	v_bfe_u32 v130, v127, 16, 1
	v_add3_u32 v127, v127, v130, s52
	ds_write_b16_d16_hi v125, v127 offset:18432
	v_mul_f32_e32 v129, v126, v129
	v_bfe_u32 v130, v129, 16, 1
	v_add3_u32 v129, v129, v130, s52
	ds_write_b16_d16_hi v125, v129 offset:9216
	v_add_u32_e32 v88, 0x800, v3
	v_ashrrev_i32_e32 v89, 6, v88
	v_lshlrev_b32_e32 v90, 2, v89
	ds_read_b32 v91, v90 offset:28672
	ds_read2st64_b32 v[92:93], v90 offset0:110 offset1:111
	ds_read2st64_b32 v[94:95], v90 offset0:108 offset1:109
	v_add_lshl_u32 v89, v89, v2, 1
	v_add_u32_e32 v100, 0x900, v3
	v_ashrrev_i32_e32 v101, 6, v100
	v_lshlrev_b32_e32 v102, 2, v101
	ds_read_b32 v103, v102 offset:28672
	ds_read2st64_b32 v[104:105], v102 offset0:110 offset1:111
	ds_read2st64_b32 v[106:107], v102 offset0:108 offset1:109
	v_add_lshl_u32 v101, v101, v2, 1
	v_add_u32_e32 v112, 0xa00, v3
	v_ashrrev_i32_e32 v113, 6, v112
	v_lshlrev_b32_e32 v114, 2, v113
	ds_read_b32 v115, v114 offset:28672
	ds_read2st64_b32 v[116:117], v114 offset0:110 offset1:111
	ds_read2st64_b32 v[118:119], v114 offset0:108 offset1:109
	v_add_lshl_u32 v113, v113, v2, 1
	v_add_u32_e32 v124, 0xb00, v3
	v_ashrrev_i32_e32 v125, 6, v124
	v_lshlrev_b32_e32 v126, 2, v125
	ds_read_b32 v127, v126 offset:28672
	ds_read2st64_b32 v[128:129], v126 offset0:110 offset1:111
	ds_read2st64_b32 v[130:131], v126 offset0:108 offset1:109
	v_add_lshl_u32 v125, v125, v2, 1
	s_waitcnt lgkmcnt(11)
	v_mov_b32_e32 v96, v91
	v_ashrrev_i32_e32 v97, 31, v91
	v_lshlrev_b64 v[96:97], 11, v[96:97]
	v_lshl_add_u64 v[96:97], s[12:13], 0, v[96:97]
	v_lshl_add_u64 v[98:99], v[96:97], 0, s[20:21]
	v_lshl_add_u64 v[98:99], v[98:99], 0, v[148:149]
	global_load_dword v90, v[98:99], off
	v_lshl_add_u64 v[96:97], v[96:97], 0, s[10:11]
	v_lshl_add_u64 v[96:97], v[96:97], 0, v[148:149]
	global_load_dword v91, v[96:97], off offset:1024
	s_waitcnt lgkmcnt(9)
	v_sub_f32_e32 v94, v32, v94
	v_mul_f32_e32 v94, 0x3fb8aa3b, v94
	v_exp_f32_e32 v94, v94
	v_sub_f32_e32 v95, v33, v95
	v_mul_f32_e32 v95, 0x3fb8aa3b, v95
	v_exp_f32_e32 v95, v95
	v_mul_f32_e32 v92, v92, v94
	v_mul_f32_e32 v93, v93, v95
	s_waitcnt lgkmcnt(8)
	v_mov_b32_e32 v108, v103
	v_ashrrev_i32_e32 v109, 31, v103
	v_lshlrev_b64 v[108:109], 11, v[108:109]
	v_lshl_add_u64 v[108:109], s[12:13], 0, v[108:109]
	v_lshl_add_u64 v[110:111], v[108:109], 0, s[20:21]
	v_lshl_add_u64 v[110:111], v[110:111], 0, v[148:149]
	global_load_dword v102, v[110:111], off
	v_lshl_add_u64 v[108:109], v[108:109], 0, s[10:11]
	v_lshl_add_u64 v[108:109], v[108:109], 0, v[148:149]
	global_load_dword v103, v[108:109], off offset:1024
	s_waitcnt lgkmcnt(6)
	v_sub_f32_e32 v106, v32, v106
	v_mul_f32_e32 v106, 0x3fb8aa3b, v106
	v_exp_f32_e32 v106, v106
	v_sub_f32_e32 v107, v33, v107
	v_mul_f32_e32 v107, 0x3fb8aa3b, v107
	v_exp_f32_e32 v107, v107
	v_mul_f32_e32 v104, v104, v106
	v_mul_f32_e32 v105, v105, v107
	s_waitcnt lgkmcnt(5)
	v_mov_b32_e32 v120, v115
	v_ashrrev_i32_e32 v121, 31, v115
	v_lshlrev_b64 v[120:121], 11, v[120:121]
	v_lshl_add_u64 v[120:121], s[12:13], 0, v[120:121]
	v_lshl_add_u64 v[122:123], v[120:121], 0, s[20:21]
	v_lshl_add_u64 v[122:123], v[122:123], 0, v[148:149]
	global_load_dword v114, v[122:123], off
	v_lshl_add_u64 v[120:121], v[120:121], 0, s[10:11]
	v_lshl_add_u64 v[120:121], v[120:121], 0, v[148:149]
	global_load_dword v115, v[120:121], off offset:1024
	s_waitcnt lgkmcnt(3)
	v_sub_f32_e32 v118, v32, v118
	v_mul_f32_e32 v118, 0x3fb8aa3b, v118
	v_exp_f32_e32 v118, v118
	v_sub_f32_e32 v119, v33, v119
	v_mul_f32_e32 v119, 0x3fb8aa3b, v119
	v_exp_f32_e32 v119, v119
	v_mul_f32_e32 v116, v116, v118
	v_mul_f32_e32 v117, v117, v119
	s_waitcnt lgkmcnt(2)
	v_mov_b32_e32 v132, v127
	v_ashrrev_i32_e32 v133, 31, v127
	v_lshlrev_b64 v[132:133], 11, v[132:133]
	v_lshl_add_u64 v[132:133], s[12:13], 0, v[132:133]
	v_lshl_add_u64 v[134:135], v[132:133], 0, s[20:21]
	v_lshl_add_u64 v[134:135], v[134:135], 0, v[148:149]
	global_load_dword v126, v[134:135], off
	v_lshl_add_u64 v[132:133], v[132:133], 0, s[10:11]
	v_lshl_add_u64 v[132:133], v[132:133], 0, v[148:149]
	global_load_dword v127, v[132:133], off offset:1024
	s_waitcnt lgkmcnt(0)
	v_sub_f32_e32 v130, v32, v130
	v_mul_f32_e32 v130, 0x3fb8aa3b, v130
	v_exp_f32_e32 v130, v130
	v_sub_f32_e32 v131, v33, v131
	v_mul_f32_e32 v131, 0x3fb8aa3b, v131
	v_exp_f32_e32 v131, v131
	v_mul_f32_e32 v128, v128, v130
	v_mul_f32_e32 v129, v129, v131
	s_waitcnt vmcnt(7)
	v_mul_f32_e32 v92, v90, v92
	v_bfe_u32 v94, v92, 16, 1
	v_add3_u32 v92, v92, v94, s52
	ds_write_b16_d16_hi v89, v92
	s_waitcnt vmcnt(6)
	v_bfe_u32 v94, v91, 16, 1
	v_add3_u32 v91, v91, v94, s52
	ds_write_b16_d16_hi v89, v91 offset:18432
	v_mul_f32_e32 v93, v90, v93
	v_bfe_u32 v94, v93, 16, 1
	v_add3_u32 v93, v93, v94, s52
	ds_write_b16_d16_hi v89, v93 offset:9216
	s_waitcnt vmcnt(5)
	v_mul_f32_e32 v104, v102, v104
	v_bfe_u32 v106, v104, 16, 1
	v_add3_u32 v104, v104, v106, s52
	ds_write_b16_d16_hi v101, v104
	s_waitcnt vmcnt(4)
	v_bfe_u32 v106, v103, 16, 1
	v_add3_u32 v103, v103, v106, s52
	ds_write_b16_d16_hi v101, v103 offset:18432
	v_mul_f32_e32 v105, v102, v105
	v_bfe_u32 v106, v105, 16, 1
	v_add3_u32 v105, v105, v106, s52
	ds_write_b16_d16_hi v101, v105 offset:9216
	s_waitcnt vmcnt(3)
	v_mul_f32_e32 v116, v114, v116
	v_bfe_u32 v118, v116, 16, 1
	v_add3_u32 v116, v116, v118, s52
	ds_write_b16_d16_hi v113, v116
	s_waitcnt vmcnt(2)
	v_bfe_u32 v118, v115, 16, 1
	v_add3_u32 v115, v115, v118, s52
	ds_write_b16_d16_hi v113, v115 offset:18432
	v_mul_f32_e32 v117, v114, v117
	v_bfe_u32 v118, v117, 16, 1
	v_add3_u32 v117, v117, v118, s52
	ds_write_b16_d16_hi v113, v117 offset:9216
	s_waitcnt vmcnt(1)
	v_mul_f32_e32 v128, v126, v128
	v_bfe_u32 v130, v128, 16, 1
	v_add3_u32 v128, v128, v130, s52
	ds_write_b16_d16_hi v125, v128
	s_waitcnt vmcnt(0)
	v_bfe_u32 v130, v127, 16, 1
	v_add3_u32 v127, v127, v130, s52
	ds_write_b16_d16_hi v125, v127 offset:18432
	v_mul_f32_e32 v129, v126, v129
	v_bfe_u32 v130, v129, 16, 1
	v_add3_u32 v129, v129, v130, s52
	ds_write_b16_d16_hi v125, v129 offset:9216
	v_add_u32_e32 v88, 0xc00, v3
	v_ashrrev_i32_e32 v89, 6, v88
	v_lshlrev_b32_e32 v90, 2, v89
	ds_read_b32 v91, v90 offset:28672
	ds_read2st64_b32 v[92:93], v90 offset0:110 offset1:111
	ds_read2st64_b32 v[94:95], v90 offset0:108 offset1:109
	v_add_lshl_u32 v89, v89, v2, 1
	v_add_u32_e32 v100, 0xd00, v3
	v_ashrrev_i32_e32 v101, 6, v100
	v_lshlrev_b32_e32 v102, 2, v101
	ds_read_b32 v103, v102 offset:28672
	ds_read2st64_b32 v[104:105], v102 offset0:110 offset1:111
	ds_read2st64_b32 v[106:107], v102 offset0:108 offset1:109
	v_add_lshl_u32 v101, v101, v2, 1
	v_add_u32_e32 v112, 0xe00, v3
	v_ashrrev_i32_e32 v113, 6, v112
	v_lshlrev_b32_e32 v114, 2, v113
	ds_read_b32 v115, v114 offset:28672
	ds_read2st64_b32 v[116:117], v114 offset0:110 offset1:111
	ds_read2st64_b32 v[118:119], v114 offset0:108 offset1:109
	v_add_lshl_u32 v113, v113, v2, 1
	v_add_u32_e32 v124, 0xf00, v3
	v_ashrrev_i32_e32 v125, 6, v124
	v_lshlrev_b32_e32 v126, 2, v125
	ds_read_b32 v127, v126 offset:28672
	ds_read2st64_b32 v[128:129], v126 offset0:110 offset1:111
	ds_read2st64_b32 v[130:131], v126 offset0:108 offset1:109
	v_add_lshl_u32 v125, v125, v2, 1
	s_waitcnt lgkmcnt(11)
	v_mov_b32_e32 v96, v91
	v_ashrrev_i32_e32 v97, 31, v91
	v_lshlrev_b64 v[96:97], 11, v[96:97]
	v_lshl_add_u64 v[96:97], s[12:13], 0, v[96:97]
	v_lshl_add_u64 v[98:99], v[96:97], 0, s[20:21]
	v_lshl_add_u64 v[98:99], v[98:99], 0, v[148:149]
	global_load_dword v90, v[98:99], off
	v_lshl_add_u64 v[96:97], v[96:97], 0, s[10:11]
	v_lshl_add_u64 v[96:97], v[96:97], 0, v[148:149]
	global_load_dword v91, v[96:97], off offset:1024
	s_waitcnt lgkmcnt(9)
	v_sub_f32_e32 v94, v32, v94
	v_mul_f32_e32 v94, 0x3fb8aa3b, v94
	v_exp_f32_e32 v94, v94
	v_sub_f32_e32 v95, v33, v95
	v_mul_f32_e32 v95, 0x3fb8aa3b, v95
	v_exp_f32_e32 v95, v95
	v_mul_f32_e32 v92, v92, v94
	v_mul_f32_e32 v93, v93, v95
	s_waitcnt lgkmcnt(8)
	v_mov_b32_e32 v108, v103
	v_ashrrev_i32_e32 v109, 31, v103
	v_lshlrev_b64 v[108:109], 11, v[108:109]
	v_lshl_add_u64 v[108:109], s[12:13], 0, v[108:109]
	v_lshl_add_u64 v[110:111], v[108:109], 0, s[20:21]
	v_lshl_add_u64 v[110:111], v[110:111], 0, v[148:149]
	global_load_dword v102, v[110:111], off
	v_lshl_add_u64 v[108:109], v[108:109], 0, s[10:11]
	v_lshl_add_u64 v[108:109], v[108:109], 0, v[148:149]
	global_load_dword v103, v[108:109], off offset:1024
	s_waitcnt lgkmcnt(6)
	v_sub_f32_e32 v106, v32, v106
	v_mul_f32_e32 v106, 0x3fb8aa3b, v106
	v_exp_f32_e32 v106, v106
	v_sub_f32_e32 v107, v33, v107
	v_mul_f32_e32 v107, 0x3fb8aa3b, v107
	v_exp_f32_e32 v107, v107
	v_mul_f32_e32 v104, v104, v106
	v_mul_f32_e32 v105, v105, v107
	s_waitcnt lgkmcnt(5)
	v_mov_b32_e32 v120, v115
	v_ashrrev_i32_e32 v121, 31, v115
	v_lshlrev_b64 v[120:121], 11, v[120:121]
	v_lshl_add_u64 v[120:121], s[12:13], 0, v[120:121]
	v_lshl_add_u64 v[122:123], v[120:121], 0, s[20:21]
	v_lshl_add_u64 v[122:123], v[122:123], 0, v[148:149]
	global_load_dword v114, v[122:123], off
	v_lshl_add_u64 v[120:121], v[120:121], 0, s[10:11]
	v_lshl_add_u64 v[120:121], v[120:121], 0, v[148:149]
	global_load_dword v115, v[120:121], off offset:1024
	s_waitcnt lgkmcnt(3)
	v_sub_f32_e32 v118, v32, v118
	v_mul_f32_e32 v118, 0x3fb8aa3b, v118
	v_exp_f32_e32 v118, v118
	v_sub_f32_e32 v119, v33, v119
	v_mul_f32_e32 v119, 0x3fb8aa3b, v119
	v_exp_f32_e32 v119, v119
	v_mul_f32_e32 v116, v116, v118
	v_mul_f32_e32 v117, v117, v119
	s_waitcnt lgkmcnt(2)
	v_mov_b32_e32 v132, v127
	v_ashrrev_i32_e32 v133, 31, v127
	v_lshlrev_b64 v[132:133], 11, v[132:133]
	v_lshl_add_u64 v[132:133], s[12:13], 0, v[132:133]
	v_lshl_add_u64 v[134:135], v[132:133], 0, s[20:21]
	v_lshl_add_u64 v[134:135], v[134:135], 0, v[148:149]
	global_load_dword v126, v[134:135], off
	v_lshl_add_u64 v[132:133], v[132:133], 0, s[10:11]
	v_lshl_add_u64 v[132:133], v[132:133], 0, v[148:149]
	global_load_dword v127, v[132:133], off offset:1024
	s_waitcnt lgkmcnt(0)
	v_sub_f32_e32 v130, v32, v130
	v_mul_f32_e32 v130, 0x3fb8aa3b, v130
	v_exp_f32_e32 v130, v130
	v_sub_f32_e32 v131, v33, v131
	v_mul_f32_e32 v131, 0x3fb8aa3b, v131
	v_exp_f32_e32 v131, v131
	v_mul_f32_e32 v128, v128, v130
	v_mul_f32_e32 v129, v129, v131
	s_waitcnt vmcnt(7)
	v_mul_f32_e32 v92, v90, v92
	v_bfe_u32 v94, v92, 16, 1
	v_add3_u32 v92, v92, v94, s52
	ds_write_b16_d16_hi v89, v92
	s_waitcnt vmcnt(6)
	v_bfe_u32 v94, v91, 16, 1
	v_add3_u32 v91, v91, v94, s52
	ds_write_b16_d16_hi v89, v91 offset:18432
	v_mul_f32_e32 v93, v90, v93
	v_bfe_u32 v94, v93, 16, 1
	v_add3_u32 v93, v93, v94, s52
	ds_write_b16_d16_hi v89, v93 offset:9216
	s_waitcnt vmcnt(5)
	v_mul_f32_e32 v104, v102, v104
	v_bfe_u32 v106, v104, 16, 1
	v_add3_u32 v104, v104, v106, s52
	ds_write_b16_d16_hi v101, v104
	s_waitcnt vmcnt(4)
	v_bfe_u32 v106, v103, 16, 1
	v_add3_u32 v103, v103, v106, s52
	ds_write_b16_d16_hi v101, v103 offset:18432
	v_mul_f32_e32 v105, v102, v105
	v_bfe_u32 v106, v105, 16, 1
	v_add3_u32 v105, v105, v106, s52
	ds_write_b16_d16_hi v101, v105 offset:9216
	s_waitcnt vmcnt(3)
	v_mul_f32_e32 v116, v114, v116
	v_bfe_u32 v118, v116, 16, 1
	v_add3_u32 v116, v116, v118, s52
	ds_write_b16_d16_hi v113, v116
	s_waitcnt vmcnt(2)
	v_bfe_u32 v118, v115, 16, 1
	v_add3_u32 v115, v115, v118, s52
	ds_write_b16_d16_hi v113, v115 offset:18432
	v_mul_f32_e32 v117, v114, v117
	v_bfe_u32 v118, v117, 16, 1
	v_add3_u32 v117, v117, v118, s52
	ds_write_b16_d16_hi v113, v117 offset:9216
	s_waitcnt vmcnt(1)
	v_mul_f32_e32 v128, v126, v128
	v_bfe_u32 v130, v128, 16, 1
	v_add3_u32 v128, v128, v130, s52
	ds_write_b16_d16_hi v125, v128
	s_waitcnt vmcnt(0)
	v_bfe_u32 v130, v127, 16, 1
	v_add3_u32 v127, v127, v130, s52
	ds_write_b16_d16_hi v125, v127 offset:18432
	v_mul_f32_e32 v129, v126, v129
	v_bfe_u32 v130, v129, 16, 1
	v_add3_u32 v129, v129, v130, s52
	ds_write_b16_d16_hi v125, v129 offset:9216
